# gelu peepholes: select at 188 of 192 sites (carry-out operands modelled as definitions, which unlocked the per-column U-gelu sites of the 4x executed group loop), abs at 173; hazard pass kept
# baseline (speedup 1.0000x reference)
.LBB0_452:
	s_waitcnt vmcnt(15)
	v_lshlrev_b32_e32 v8, 16, v36
	v_and_b32_e32 v9, 0xffff0000, v36
	v_fma_f32 v10, |v8|, s40, 1.0
	v_fma_f32 v11, |v9|, s40, 1.0
	v_mov_b64_e32 v[12:13], s[44:45]
	v_rcp_f32_e32 v10, v10
	v_rcp_f32_e32 v11, v11
	v_pk_mul_f32 v[16:17], v[8:9], v[8:9]
	v_pk_mul_f32 v[16:17], v[16:17], s[64:65] op_sel_hi:[1,0]
	v_pk_fma_f32 v[14:15], v[10:11], s[42:43], v[12:13] op_sel_hi:[1,0,0]
	v_exp_f32_e32 v16, v16
	v_pk_fma_f32 v[14:15], v[10:11], v[14:15], s[48:49] op_sel_hi:[1,1,0]
	v_exp_f32_e32 v17, v17
	v_pk_fma_f32 v[14:15], v[10:11], v[14:15], s[50:51] op_sel_hi:[1,1,0]
	v_add_f32_e32 v4, v72, v4
	v_pk_fma_f32 v[14:15], v[10:11], v[14:15], s[56:57] op_sel_hi:[1,1,0]
	s_mov_b32 s0, 0x1506e000
	v_pk_mul_f32 v[10:11], v[10:11], v[14:15]
	s_add_u32 s70, s70, 0x400
	v_pk_mul_f32 v[10:11], v[16:17], v[10:11]
	v_lshlrev_b32_e32 v16, 16, v37
	v_and_b32_e32 v17, 0xffff0000, v37
	v_fma_f32 v18, |v16|, s40, 1.0
	v_fma_f32 v19, |v17|, s40, 1.0
	v_rcp_f32_e32 v18, v18
	v_rcp_f32_e32 v19, v19
	v_max_f32_e32 v80, 0, v8
	v_fma_f32 v3, -|v8|, v10, v80
	v_max_f32_e32 v81, 0, v9
	v_fma_f32 v14, -|v9|, v11, v81
	s_addc_u32 s71, s71, 0
	v_pk_fma_f32 v[8:9], v[18:19], s[42:43], v[12:13] op_sel_hi:[1,0,0]
	v_mul_f32_e32 v3, v3, v4
	v_pk_mul_f32 v[10:11], v[16:17], v[16:17]
	v_pk_fma_f32 v[8:9], v[18:19], v[8:9], s[48:49] op_sel_hi:[1,1,0]
	v_pk_mul_f32 v[10:11], v[10:11], s[64:65] op_sel_hi:[1,0]
	v_pk_fma_f32 v[8:9], v[18:19], v[8:9], s[50:51] op_sel_hi:[1,1,0]
	v_exp_f32_e32 v10, v10
	v_exp_f32_e32 v11, v11
	v_pk_fma_f32 v[8:9], v[18:19], v[8:9], s[56:57] op_sel_hi:[1,1,0]
	v_pk_mul_f32 v[8:9], v[18:19], v[8:9]
	v_add_f32_e32 v4, v72, v5
	v_pk_mul_f32 v[8:9], v[10:11], v[8:9]
	v_mul_f32_e32 v4, v14, v4
	v_max_f32_e32 v82, 0, v16
	v_fma_f32 v8, -|v16|, v8, v82
	v_max_f32_e32 v83, 0, v17
	v_fma_f32 v9, -|v17|, v9, v83
	v_cvt_pk_bf16_f32 v4, v3, v4
	v_add_f32_e32 v3, v72, v6
	v_add_f32_e32 v5, v72, v7
	v_lshl_add_u64 v[26:27], v[26:27], 0, s[68:69]
	v_add_co_u32_e32 v6, vcc, s0, v34
	s_mov_b64 s[0:1], 0x8000
	v_mul_f32_e32 v5, v9, v5
	v_addc_co_u32_e32 v7, vcc, 0, v35, vcc
	v_lshl_add_u64 v[28:29], v[28:29], 0, s[0:1]
	v_lshl_add_u64 v[30:31], v[30:31], 0, s[68:69]
	s_cmpk_eq_i32 s70, 0x1000
	v_lshl_add_u64 v[32:33], v[32:33], 0, s[68:69]
	v_mul_f32_e32 v3, v8, v3
	v_cvt_pk_bf16_f32 v5, v3, v5
	global_store_dwordx2 v[6:7], v[4:5], off offset:480
	s_barrier
	s_cbranch_scc1 .LBB0_410
.LBB0_453:
	v_lshl_add_u64 v[4:5], s[12:13], 0, v[32:33]
	v_add_co_u32_e32 v18, vcc, 0x696e000, v4
	s_add_u32 s0, s16, s70
	s_nop 0
	v_addc_co_u32_e32 v19, vcc, 0, v5, vcc
	global_load_dwordx4 v[8:11], v[18:19], off
	global_load_dwordx4 v[4:7], v[18:19], off offset:2048
	s_addc_u32 s1, s38, s71
	s_add_u32 s4, s88, s70
	s_addc_u32 s5, s89, s71
	global_load_dwordx2 v[20:21], v2, s[0:1]
	global_load_dwordx2 v[22:23], v2, s[4:5]
	v_mov_b64_e32 v[16:17], s[44:45]
	ds_read_b64 v[14:15], v68
	ds_read_b64 v[12:13], v69
	s_waitcnt vmcnt(3)
	v_lshlrev_b32_e32 v24, 16, v8
	v_and_b32_e32 v25, 0xffff0000, v8
	s_waitcnt vmcnt(2)
	v_lshlrev_b32_e32 v34, 16, v4
	v_and_b32_e32 v35, 0xffff0000, v4
	v_fma_f32 v36, |v24|, s40, 1.0
	v_fma_f32 v37, |v25|, s40, 1.0
	v_fma_f32 v40, |v34|, s40, 1.0
	v_fma_f32 v41, |v35|, s40, 1.0
	v_rcp_f32_e32 v36, v36
	v_rcp_f32_e32 v37, v37
	v_rcp_f32_e32 v40, v40
	v_rcp_f32_e32 v41, v41
	v_pk_mul_f32 v[38:39], v[24:25], v[24:25]
	v_pk_mul_f32 v[42:43], v[34:35], v[34:35]
	v_pk_mul_f32 v[38:39], v[38:39], s[64:65] op_sel_hi:[1,0]
	v_pk_fma_f32 v[44:45], v[36:37], s[42:43], v[16:17] op_sel_hi:[1,0,0]
	v_pk_mul_f32 v[42:43], v[42:43], s[64:65] op_sel_hi:[1,0]
	v_exp_f32_e32 v38, v38
	v_exp_f32_e32 v39, v39
	v_pk_fma_f32 v[46:47], v[40:41], s[42:43], v[16:17] op_sel_hi:[1,0,0]
	v_pk_fma_f32 v[44:45], v[36:37], v[44:45], s[48:49] op_sel_hi:[1,1,0]
	v_exp_f32_e32 v42, v42
	v_exp_f32_e32 v43, v43
	v_pk_fma_f32 v[46:47], v[40:41], v[46:47], s[48:49] op_sel_hi:[1,1,0]
	v_pk_fma_f32 v[44:45], v[36:37], v[44:45], s[50:51] op_sel_hi:[1,1,0]
	v_pk_fma_f32 v[46:47], v[40:41], v[46:47], s[50:51] op_sel_hi:[1,1,0]
	v_pk_fma_f32 v[44:45], v[36:37], v[44:45], s[56:57] op_sel_hi:[1,1,0]
	v_pk_fma_f32 v[46:47], v[40:41], v[46:47], s[56:57] op_sel_hi:[1,1,0]
	v_pk_mul_f32 v[36:37], v[36:37], v[44:45]
	v_pk_mul_f32 v[40:41], v[40:41], v[46:47]
	v_pk_mul_f32 v[36:37], v[38:39], v[36:37]
	v_pk_mul_f32 v[38:39], v[42:43], v[40:41]
	v_max_f32_e32 v84, 0, v24
	v_fma_f32 v3, -|v24|, v36, v84
	v_max_f32_e32 v85, 0, v25
	s_waitcnt lgkmcnt(1)
	v_sub_f32_e32 v3, v3, v14
	s_waitcnt lgkmcnt(0)
	v_mul_f32_e32 v3, v12, v3
	v_fma_f32 v4, -|v25|, v37, v85
	v_max_f32_e32 v86, 0, v34
	v_sub_f32_e32 v4, v4, v14
	v_mul_f32_e32 v4, v12, v4
	v_fma_f32 v8, -|v34|, v38, v86
	v_max_f32_e32 v90, 0, v35
	v_sub_f32_e32 v8, v8, v15
	v_mul_f32_e32 v8, v13, v8
	v_fma_f32 v24, -|v35|, v39, v90
	v_sub_f32_e32 v24, v24, v15
	v_mul_f32_e32 v24, v13, v24
	s_waitcnt vmcnt(0)
	v_fma_f32 v3, v20, v3, v22
	v_fma_f32 v4, v21, v4, v23
	v_fma_f32 v8, v20, v8, v22
	v_fmac_f32_e32 v23, v21, v24
	v_cvt_pk_bf16_f32 v3, v3, v8
	ds_write_b32 v70, v3
	v_cvt_pk_bf16_f32 v3, v4, v23
	global_load_dwordx2 v[22:23], v2, s[0:1] offset:8
	global_load_dwordx2 v[20:21], v2, s[4:5] offset:8
	v_lshlrev_b32_e32 v8, 16, v9
	v_and_b32_e32 v9, 0xffff0000, v9
	v_lshlrev_b32_e32 v4, 16, v5
	v_and_b32_e32 v5, 0xffff0000, v5
	v_fma_f32 v24, |v8|, s40, 1.0
	v_fma_f32 v25, |v9|, s40, 1.0
	v_fma_f32 v36, |v4|, s40, 1.0
	v_fma_f32 v37, |v5|, s40, 1.0
	v_rcp_f32_e32 v24, v24
	v_rcp_f32_e32 v25, v25
	v_rcp_f32_e32 v36, v36
	v_rcp_f32_e32 v37, v37
	v_pk_mul_f32 v[34:35], v[8:9], v[8:9]
	v_pk_mul_f32 v[38:39], v[4:5], v[4:5]
	v_pk_mul_f32 v[34:35], v[34:35], s[64:65] op_sel_hi:[1,0]
	v_pk_fma_f32 v[40:41], v[24:25], s[42:43], v[16:17] op_sel_hi:[1,0,0]
	v_pk_mul_f32 v[38:39], v[38:39], s[64:65] op_sel_hi:[1,0]
	v_exp_f32_e32 v34, v34
	v_exp_f32_e32 v35, v35
	v_pk_fma_f32 v[42:43], v[36:37], s[42:43], v[16:17] op_sel_hi:[1,0,0]
	v_pk_fma_f32 v[40:41], v[24:25], v[40:41], s[48:49] op_sel_hi:[1,1,0]
	v_exp_f32_e32 v38, v38
	v_exp_f32_e32 v39, v39
	v_pk_fma_f32 v[42:43], v[36:37], v[42:43], s[48:49] op_sel_hi:[1,1,0]
	v_pk_fma_f32 v[40:41], v[24:25], v[40:41], s[50:51] op_sel_hi:[1,1,0]
	v_pk_fma_f32 v[42:43], v[36:37], v[42:43], s[50:51] op_sel_hi:[1,1,0]
	v_pk_fma_f32 v[40:41], v[24:25], v[40:41], s[56:57] op_sel_hi:[1,1,0]
	v_pk_fma_f32 v[42:43], v[36:37], v[42:43], s[56:57] op_sel_hi:[1,1,0]
	v_pk_mul_f32 v[24:25], v[24:25], v[40:41]
	v_pk_mul_f32 v[36:37], v[36:37], v[42:43]
	v_pk_mul_f32 v[24:25], v[34:35], v[24:25]
	v_pk_mul_f32 v[34:35], v[38:39], v[36:37]
	v_max_f32_e32 v91, 0, v8
	v_fma_f32 v8, -|v8|, v24, v91
	v_max_f32_e32 v92, 0, v9
	v_fma_f32 v9, -|v9|, v25, v92
	v_max_f32_e32 v93, 0, v4
	v_fma_f32 v4, -|v4|, v34, v93
	v_max_f32_e32 v94, 0, v5
	v_fma_f32 v5, -|v5|, v35, v94
	v_sub_f32_e32 v8, v8, v14
	v_mul_f32_e32 v8, v12, v8
	v_sub_f32_e32 v9, v9, v14
	v_mul_f32_e32 v9, v12, v9
	v_sub_f32_e32 v4, v4, v15
	v_mul_f32_e32 v4, v13, v4
	v_sub_f32_e32 v5, v5, v15
	ds_write_b32 v70, v3 offset:272
	v_mul_f32_e32 v5, v13, v5
	s_waitcnt vmcnt(0)
	v_fma_f32 v3, v22, v8, v20
	v_fma_f32 v8, v23, v9, v21
	v_fma_f32 v4, v22, v4, v20
	v_cvt_pk_bf16_f32 v3, v3, v4
	v_fmac_f32_e32 v21, v23, v5
	ds_write_b32 v70, v3 offset:544
	v_cvt_pk_bf16_f32 v3, v8, v21
	global_load_dwordx2 v[8:9], v2, s[0:1] offset:16
	global_load_dwordx2 v[4:5], v2, s[4:5] offset:16
	v_lshlrev_b32_e32 v20, 16, v10
	v_and_b32_e32 v21, 0xffff0000, v10
	v_lshlrev_b32_e32 v22, 16, v6
	v_and_b32_e32 v23, 0xffff0000, v6
	v_fma_f32 v24, |v20|, s40, 1.0
	v_fma_f32 v25, |v21|, s40, 1.0
	v_fma_f32 v36, |v22|, s40, 1.0
	v_fma_f32 v37, |v23|, s40, 1.0
	v_rcp_f32_e32 v24, v24
	v_rcp_f32_e32 v25, v25
	v_rcp_f32_e32 v36, v36
	v_rcp_f32_e32 v37, v37
	v_pk_mul_f32 v[34:35], v[20:21], v[20:21]
	v_pk_mul_f32 v[38:39], v[22:23], v[22:23]
	v_pk_mul_f32 v[34:35], v[34:35], s[64:65] op_sel_hi:[1,0]
	v_pk_fma_f32 v[40:41], v[24:25], s[42:43], v[16:17] op_sel_hi:[1,0,0]
	v_pk_mul_f32 v[38:39], v[38:39], s[64:65] op_sel_hi:[1,0]
	v_exp_f32_e32 v34, v34
	v_exp_f32_e32 v35, v35
	v_pk_fma_f32 v[42:43], v[36:37], s[42:43], v[16:17] op_sel_hi:[1,0,0]
	v_pk_fma_f32 v[40:41], v[24:25], v[40:41], s[48:49] op_sel_hi:[1,1,0]
	v_exp_f32_e32 v38, v38
	v_exp_f32_e32 v39, v39
	v_pk_fma_f32 v[42:43], v[36:37], v[42:43], s[48:49] op_sel_hi:[1,1,0]
	v_pk_fma_f32 v[40:41], v[24:25], v[40:41], s[50:51] op_sel_hi:[1,1,0]
	v_pk_fma_f32 v[42:43], v[36:37], v[42:43], s[50:51] op_sel_hi:[1,1,0]
	v_pk_fma_f32 v[40:41], v[24:25], v[40:41], s[56:57] op_sel_hi:[1,1,0]
	v_pk_fma_f32 v[42:43], v[36:37], v[42:43], s[56:57] op_sel_hi:[1,1,0]
	v_pk_mul_f32 v[24:25], v[24:25], v[40:41]
	v_pk_mul_f32 v[36:37], v[36:37], v[42:43]
	v_pk_mul_f32 v[24:25], v[34:35], v[24:25]
	v_pk_mul_f32 v[34:35], v[38:39], v[36:37]
	v_max_f32_e32 v95, 0, v20
	v_fma_f32 v6, -|v20|, v24, v95
	v_max_f32_e32 v96, 0, v21
	v_fma_f32 v10, -|v21|, v25, v96
	v_max_f32_e32 v97, 0, v22
	v_fma_f32 v20, -|v22|, v34, v97
	v_max_f32_e32 v98, 0, v23
	v_fma_f32 v21, -|v23|, v35, v98
	v_sub_f32_e32 v6, v6, v14
	v_mul_f32_e32 v6, v12, v6
	v_sub_f32_e32 v10, v10, v14
	v_mul_f32_e32 v10, v12, v10
	v_sub_f32_e32 v20, v20, v15
	v_mul_f32_e32 v20, v13, v20
	v_sub_f32_e32 v21, v21, v15
	v_mul_f32_e32 v21, v13, v21
	ds_write_b32 v70, v3 offset:816
	s_waitcnt vmcnt(0)
	v_fma_f32 v3, v8, v6, v4
	v_fma_f32 v6, v9, v10, v5
	v_fma_f32 v4, v8, v20, v4
	v_fmac_f32_e32 v5, v9, v21
	v_cvt_pk_bf16_f32 v3, v3, v4
	ds_write_b32 v70, v3 offset:1088
	v_cvt_pk_bf16_f32 v3, v6, v5
	global_load_dwordx2 v[8:9], v2, s[0:1] offset:24
	global_load_dwordx2 v[4:5], v2, s[4:5] offset:24
	v_lshlrev_b32_e32 v10, 16, v11
	v_and_b32_e32 v11, 0xffff0000, v11
	v_lshlrev_b32_e32 v6, 16, v7
	v_and_b32_e32 v7, 0xffff0000, v7
	v_fma_f32 v20, |v10|, s40, 1.0
	v_fma_f32 v21, |v11|, s40, 1.0
	v_fma_f32 v24, |v6|, s40, 1.0
	v_fma_f32 v25, |v7|, s40, 1.0
	v_rcp_f32_e32 v20, v20
	v_rcp_f32_e32 v21, v21
	v_rcp_f32_e32 v24, v24
	v_rcp_f32_e32 v25, v25
	v_pk_mul_f32 v[22:23], v[10:11], v[10:11]
	v_pk_mul_f32 v[34:35], v[6:7], v[6:7]
	v_pk_mul_f32 v[22:23], v[22:23], s[64:65] op_sel_hi:[1,0]
	v_pk_fma_f32 v[36:37], v[20:21], s[42:43], v[16:17] op_sel_hi:[1,0,0]
	v_pk_mul_f32 v[34:35], v[34:35], s[64:65] op_sel_hi:[1,0]
	v_exp_f32_e32 v22, v22
	v_exp_f32_e32 v23, v23
	v_pk_fma_f32 v[38:39], v[24:25], s[42:43], v[16:17] op_sel_hi:[1,0,0]
	v_pk_fma_f32 v[36:37], v[20:21], v[36:37], s[48:49] op_sel_hi:[1,1,0]
	v_exp_f32_e32 v34, v34
	v_exp_f32_e32 v35, v35
	v_pk_fma_f32 v[38:39], v[24:25], v[38:39], s[48:49] op_sel_hi:[1,1,0]
	v_pk_fma_f32 v[36:37], v[20:21], v[36:37], s[50:51] op_sel_hi:[1,1,0]
	v_pk_fma_f32 v[38:39], v[24:25], v[38:39], s[50:51] op_sel_hi:[1,1,0]
	v_pk_fma_f32 v[36:37], v[20:21], v[36:37], s[56:57] op_sel_hi:[1,1,0]
	v_pk_fma_f32 v[38:39], v[24:25], v[38:39], s[56:57] op_sel_hi:[1,1,0]
	v_pk_mul_f32 v[20:21], v[20:21], v[36:37]
	v_pk_mul_f32 v[24:25], v[24:25], v[38:39]
	v_pk_mul_f32 v[20:21], v[22:23], v[20:21]
	v_pk_mul_f32 v[22:23], v[34:35], v[24:25]
	v_max_f32_e32 v99, 0, v10
	v_fma_f32 v10, -|v10|, v20, v99
	v_max_f32_e32 v100, 0, v11
	v_fma_f32 v11, -|v11|, v21, v100
	v_max_f32_e32 v104, 0, v6
	v_fma_f32 v6, -|v6|, v22, v104
	v_max_f32_e32 v105, 0, v7
	v_fma_f32 v7, -|v7|, v23, v105
	v_sub_f32_e32 v10, v10, v14
	v_mul_f32_e32 v10, v12, v10
	v_sub_f32_e32 v11, v11, v14
	v_mul_f32_e32 v11, v12, v11
	v_sub_f32_e32 v6, v6, v15
	v_mul_f32_e32 v6, v13, v6
	v_sub_f32_e32 v7, v7, v15
	v_mul_f32_e32 v7, v13, v7
	ds_write_b32 v70, v3 offset:1360
	s_waitcnt vmcnt(0)
	v_fma_f32 v3, v8, v10, v4
	v_fma_f32 v10, v9, v11, v5
	v_fma_f32 v4, v8, v6, v4
	v_fmac_f32_e32 v5, v9, v7
	v_cvt_pk_bf16_f32 v3, v3, v4
	ds_write_b32 v70, v3 offset:1632
	v_cvt_pk_bf16_f32 v3, v10, v5
	global_load_dwordx4 v[8:11], v[18:19], off offset:16
	global_load_dwordx4 v[4:7], v[18:19], off offset:2064
	global_load_dwordx2 v[22:23], v2, s[0:1] offset:32
	global_load_dwordx2 v[20:21], v2, s[4:5] offset:32
	ds_write_b32 v70, v3 offset:1904
	s_waitcnt vmcnt(3)
	v_lshlrev_b32_e32 v24, 16, v8
	v_and_b32_e32 v25, 0xffff0000, v8
	s_waitcnt vmcnt(2)
	v_lshlrev_b32_e32 v34, 16, v4
	v_and_b32_e32 v35, 0xffff0000, v4
	v_fma_f32 v36, |v24|, s40, 1.0
	v_fma_f32 v37, |v25|, s40, 1.0
	v_fma_f32 v40, |v34|, s40, 1.0
	v_fma_f32 v41, |v35|, s40, 1.0
	v_rcp_f32_e32 v36, v36
	v_rcp_f32_e32 v37, v37
	v_rcp_f32_e32 v40, v40
	v_rcp_f32_e32 v41, v41
	v_pk_mul_f32 v[38:39], v[24:25], v[24:25]
	v_pk_mul_f32 v[42:43], v[34:35], v[34:35]
	v_pk_mul_f32 v[38:39], v[38:39], s[64:65] op_sel_hi:[1,0]
	v_pk_fma_f32 v[44:45], v[36:37], s[42:43], v[16:17] op_sel_hi:[1,0,0]
	v_pk_mul_f32 v[42:43], v[42:43], s[64:65] op_sel_hi:[1,0]
	v_exp_f32_e32 v38, v38
	v_exp_f32_e32 v39, v39
	v_pk_fma_f32 v[46:47], v[40:41], s[42:43], v[16:17] op_sel_hi:[1,0,0]
	v_pk_fma_f32 v[44:45], v[36:37], v[44:45], s[48:49] op_sel_hi:[1,1,0]
	v_exp_f32_e32 v42, v42
	v_exp_f32_e32 v43, v43
	v_pk_fma_f32 v[46:47], v[40:41], v[46:47], s[48:49] op_sel_hi:[1,1,0]
	v_pk_fma_f32 v[44:45], v[36:37], v[44:45], s[50:51] op_sel_hi:[1,1,0]
	v_pk_fma_f32 v[46:47], v[40:41], v[46:47], s[50:51] op_sel_hi:[1,1,0]
	v_pk_fma_f32 v[44:45], v[36:37], v[44:45], s[56:57] op_sel_hi:[1,1,0]
	v_pk_fma_f32 v[46:47], v[40:41], v[46:47], s[56:57] op_sel_hi:[1,1,0]
	v_pk_mul_f32 v[36:37], v[36:37], v[44:45]
	v_pk_mul_f32 v[40:41], v[40:41], v[46:47]
	v_pk_mul_f32 v[36:37], v[38:39], v[36:37]
	v_pk_mul_f32 v[38:39], v[42:43], v[40:41]
	v_max_f32_e32 v106, 0, v24
	v_fma_f32 v3, -|v24|, v36, v106
	v_max_f32_e32 v107, 0, v25
	v_fma_f32 v4, -|v25|, v37, v107
	v_max_f32_e32 v108, 0, v34
	v_fma_f32 v8, -|v34|, v38, v108
	v_max_f32_e32 v109, 0, v35
	v_fma_f32 v24, -|v35|, v39, v109
	v_sub_f32_e32 v3, v3, v14
	v_mul_f32_e32 v3, v12, v3
	v_sub_f32_e32 v4, v4, v14
	v_mul_f32_e32 v4, v12, v4
	v_sub_f32_e32 v8, v8, v15
	v_mul_f32_e32 v8, v13, v8
	v_sub_f32_e32 v24, v24, v15
	v_mul_f32_e32 v24, v13, v24
	s_waitcnt vmcnt(0)
	v_fma_f32 v3, v22, v3, v20
	v_fma_f32 v4, v23, v4, v21
	v_fma_f32 v8, v22, v8, v20
	v_fmac_f32_e32 v21, v23, v24
	v_cvt_pk_bf16_f32 v3, v3, v8
	ds_write_b32 v70, v3 offset:2176
	v_cvt_pk_bf16_f32 v3, v4, v21
	global_load_dwordx2 v[22:23], v2, s[0:1] offset:40
	global_load_dwordx2 v[20:21], v2, s[4:5] offset:40
	v_lshlrev_b32_e32 v8, 16, v9
	v_and_b32_e32 v9, 0xffff0000, v9
	v_lshlrev_b32_e32 v4, 16, v5
	v_and_b32_e32 v5, 0xffff0000, v5
	v_fma_f32 v24, |v8|, s40, 1.0
	v_fma_f32 v25, |v9|, s40, 1.0
	v_fma_f32 v36, |v4|, s40, 1.0
	v_fma_f32 v37, |v5|, s40, 1.0
	v_rcp_f32_e32 v24, v24
	v_rcp_f32_e32 v25, v25
	v_rcp_f32_e32 v36, v36
	v_rcp_f32_e32 v37, v37
	v_pk_mul_f32 v[34:35], v[8:9], v[8:9]
	v_pk_mul_f32 v[38:39], v[4:5], v[4:5]
	v_pk_mul_f32 v[34:35], v[34:35], s[64:65] op_sel_hi:[1,0]
	v_pk_fma_f32 v[40:41], v[24:25], s[42:43], v[16:17] op_sel_hi:[1,0,0]
	v_pk_mul_f32 v[38:39], v[38:39], s[64:65] op_sel_hi:[1,0]
	v_exp_f32_e32 v34, v34
	v_exp_f32_e32 v35, v35
	v_pk_fma_f32 v[42:43], v[36:37], s[42:43], v[16:17] op_sel_hi:[1,0,0]
	v_pk_fma_f32 v[40:41], v[24:25], v[40:41], s[48:49] op_sel_hi:[1,1,0]
	v_exp_f32_e32 v38, v38
	v_exp_f32_e32 v39, v39
	v_pk_fma_f32 v[42:43], v[36:37], v[42:43], s[48:49] op_sel_hi:[1,1,0]
	v_pk_fma_f32 v[40:41], v[24:25], v[40:41], s[50:51] op_sel_hi:[1,1,0]
	v_pk_fma_f32 v[42:43], v[36:37], v[42:43], s[50:51] op_sel_hi:[1,1,0]
	v_pk_fma_f32 v[40:41], v[24:25], v[40:41], s[56:57] op_sel_hi:[1,1,0]
	v_pk_fma_f32 v[42:43], v[36:37], v[42:43], s[56:57] op_sel_hi:[1,1,0]
	v_pk_mul_f32 v[24:25], v[24:25], v[40:41]
	v_pk_mul_f32 v[36:37], v[36:37], v[42:43]
	v_pk_mul_f32 v[24:25], v[34:35], v[24:25]
	v_pk_mul_f32 v[34:35], v[38:39], v[36:37]
	v_max_f32_e32 v110, 0, v8
	v_fma_f32 v8, -|v8|, v24, v110
	v_max_f32_e32 v111, 0, v9
	v_fma_f32 v9, -|v9|, v25, v111
	v_max_f32_e32 v112, 0, v4
	v_fma_f32 v4, -|v4|, v34, v112
	v_max_f32_e32 v113, 0, v5
	v_fma_f32 v5, -|v5|, v35, v113
	v_sub_f32_e32 v8, v8, v14
	v_mul_f32_e32 v8, v12, v8
	v_sub_f32_e32 v9, v9, v14
	v_mul_f32_e32 v9, v12, v9
	v_sub_f32_e32 v4, v4, v15
	v_mul_f32_e32 v4, v13, v4
	v_sub_f32_e32 v5, v5, v15
	ds_write_b32 v70, v3 offset:2448
	v_mul_f32_e32 v5, v13, v5
	s_waitcnt vmcnt(0)
	v_fma_f32 v3, v22, v8, v20
	v_fma_f32 v8, v23, v9, v21
	v_fma_f32 v4, v22, v4, v20
	v_cvt_pk_bf16_f32 v3, v3, v4
	v_fmac_f32_e32 v21, v23, v5
	ds_write_b32 v70, v3 offset:2720
	v_cvt_pk_bf16_f32 v3, v8, v21
	global_load_dwordx2 v[8:9], v2, s[0:1] offset:48
	global_load_dwordx2 v[4:5], v2, s[4:5] offset:48
	v_lshlrev_b32_e32 v20, 16, v10
	v_and_b32_e32 v21, 0xffff0000, v10
	v_lshlrev_b32_e32 v22, 16, v6
	v_and_b32_e32 v23, 0xffff0000, v6
	v_fma_f32 v24, |v20|, s40, 1.0
	v_fma_f32 v25, |v21|, s40, 1.0
	v_fma_f32 v36, |v22|, s40, 1.0
	v_fma_f32 v37, |v23|, s40, 1.0
	v_rcp_f32_e32 v24, v24
	v_rcp_f32_e32 v25, v25
	v_rcp_f32_e32 v36, v36
	v_rcp_f32_e32 v37, v37
	v_pk_mul_f32 v[34:35], v[20:21], v[20:21]
	v_pk_mul_f32 v[38:39], v[22:23], v[22:23]
	v_pk_mul_f32 v[34:35], v[34:35], s[64:65] op_sel_hi:[1,0]
	v_pk_fma_f32 v[40:41], v[24:25], s[42:43], v[16:17] op_sel_hi:[1,0,0]
	v_pk_mul_f32 v[38:39], v[38:39], s[64:65] op_sel_hi:[1,0]
	v_exp_f32_e32 v34, v34
	v_exp_f32_e32 v35, v35
	v_pk_fma_f32 v[42:43], v[36:37], s[42:43], v[16:17] op_sel_hi:[1,0,0]
	v_pk_fma_f32 v[40:41], v[24:25], v[40:41], s[48:49] op_sel_hi:[1,1,0]
	v_exp_f32_e32 v38, v38
	v_exp_f32_e32 v39, v39
	v_pk_fma_f32 v[42:43], v[36:37], v[42:43], s[48:49] op_sel_hi:[1,1,0]
	v_pk_fma_f32 v[40:41], v[24:25], v[40:41], s[50:51] op_sel_hi:[1,1,0]
	v_pk_fma_f32 v[42:43], v[36:37], v[42:43], s[50:51] op_sel_hi:[1,1,0]
	v_pk_fma_f32 v[40:41], v[24:25], v[40:41], s[56:57] op_sel_hi:[1,1,0]
	v_pk_fma_f32 v[42:43], v[36:37], v[42:43], s[56:57] op_sel_hi:[1,1,0]
	v_pk_mul_f32 v[24:25], v[24:25], v[40:41]
	v_pk_mul_f32 v[36:37], v[36:37], v[42:43]
	v_pk_mul_f32 v[24:25], v[34:35], v[24:25]
	v_pk_mul_f32 v[34:35], v[38:39], v[36:37]
	v_max_f32_e32 v114, 0, v20
	v_fma_f32 v6, -|v20|, v24, v114
	v_max_f32_e32 v115, 0, v21
	v_fma_f32 v10, -|v21|, v25, v115
	v_max_f32_e32 v116, 0, v22
	v_fma_f32 v20, -|v22|, v34, v116
	v_max_f32_e32 v117, 0, v23
	v_fma_f32 v21, -|v23|, v35, v117
	v_sub_f32_e32 v6, v6, v14
	v_mul_f32_e32 v6, v12, v6
	v_sub_f32_e32 v10, v10, v14
	v_mul_f32_e32 v10, v12, v10
	v_sub_f32_e32 v20, v20, v15
	v_mul_f32_e32 v20, v13, v20
	v_sub_f32_e32 v21, v21, v15
	v_mul_f32_e32 v21, v13, v21
	ds_write_b32 v70, v3 offset:2992
	s_waitcnt vmcnt(0)
	v_fma_f32 v3, v8, v6, v4
	v_fma_f32 v6, v9, v10, v5
	v_fma_f32 v4, v8, v20, v4
	v_fmac_f32_e32 v5, v9, v21
	v_cvt_pk_bf16_f32 v3, v3, v4
	ds_write_b32 v70, v3 offset:3264
	v_cvt_pk_bf16_f32 v3, v6, v5
	global_load_dwordx2 v[8:9], v2, s[0:1] offset:56
	global_load_dwordx2 v[4:5], v2, s[4:5] offset:56
	v_lshlrev_b32_e32 v10, 16, v11
	v_and_b32_e32 v11, 0xffff0000, v11
	v_lshlrev_b32_e32 v6, 16, v7
	v_and_b32_e32 v7, 0xffff0000, v7
	v_fma_f32 v20, |v10|, s40, 1.0
	v_fma_f32 v21, |v11|, s40, 1.0
	v_fma_f32 v24, |v6|, s40, 1.0
	v_fma_f32 v25, |v7|, s40, 1.0
	v_rcp_f32_e32 v20, v20
	v_rcp_f32_e32 v21, v21
	v_rcp_f32_e32 v24, v24
	v_rcp_f32_e32 v25, v25
	v_pk_mul_f32 v[22:23], v[10:11], v[10:11]
	v_pk_mul_f32 v[34:35], v[6:7], v[6:7]
	v_pk_mul_f32 v[22:23], v[22:23], s[64:65] op_sel_hi:[1,0]
	v_pk_fma_f32 v[36:37], v[20:21], s[42:43], v[16:17] op_sel_hi:[1,0,0]
	v_pk_mul_f32 v[34:35], v[34:35], s[64:65] op_sel_hi:[1,0]
	v_exp_f32_e32 v22, v22
	v_exp_f32_e32 v23, v23
	v_pk_fma_f32 v[38:39], v[24:25], s[42:43], v[16:17] op_sel_hi:[1,0,0]
	v_pk_fma_f32 v[36:37], v[20:21], v[36:37], s[48:49] op_sel_hi:[1,1,0]
	v_exp_f32_e32 v34, v34
	v_exp_f32_e32 v35, v35
	v_pk_fma_f32 v[38:39], v[24:25], v[38:39], s[48:49] op_sel_hi:[1,1,0]
	v_pk_fma_f32 v[36:37], v[20:21], v[36:37], s[50:51] op_sel_hi:[1,1,0]
	v_pk_fma_f32 v[38:39], v[24:25], v[38:39], s[50:51] op_sel_hi:[1,1,0]
	v_pk_fma_f32 v[36:37], v[20:21], v[36:37], s[56:57] op_sel_hi:[1,1,0]
	v_pk_fma_f32 v[38:39], v[24:25], v[38:39], s[56:57] op_sel_hi:[1,1,0]
	v_pk_mul_f32 v[20:21], v[20:21], v[36:37]
	v_pk_mul_f32 v[24:25], v[24:25], v[38:39]
	v_pk_mul_f32 v[20:21], v[22:23], v[20:21]
	v_pk_mul_f32 v[22:23], v[34:35], v[24:25]
	v_max_f32_e32 v80, 0, v10
	v_fma_f32 v10, -|v10|, v20, v80
	v_max_f32_e32 v81, 0, v11
	v_fma_f32 v11, -|v11|, v21, v81
	v_max_f32_e32 v82, 0, v6
	v_fma_f32 v6, -|v6|, v22, v82
	v_max_f32_e32 v83, 0, v7
	v_fma_f32 v7, -|v7|, v23, v83
	v_sub_f32_e32 v10, v10, v14
	v_mul_f32_e32 v10, v12, v10
	v_sub_f32_e32 v11, v11, v14
	v_mul_f32_e32 v11, v12, v11
	v_sub_f32_e32 v6, v6, v15
	v_mul_f32_e32 v6, v13, v6
	v_sub_f32_e32 v7, v7, v15
	v_mul_f32_e32 v7, v13, v7
	ds_write_b32 v70, v3 offset:3536
	s_waitcnt vmcnt(0)
	v_fma_f32 v3, v8, v10, v4
	v_fma_f32 v10, v9, v11, v5
	v_fma_f32 v4, v8, v6, v4
	v_fmac_f32_e32 v5, v9, v7
	v_cvt_pk_bf16_f32 v3, v3, v4
	ds_write_b32 v70, v3 offset:3808
	v_cvt_pk_bf16_f32 v3, v10, v5
	global_load_dwordx4 v[8:11], v[18:19], off offset:32
	global_load_dwordx4 v[4:7], v[18:19], off offset:2080
	global_load_dwordx2 v[22:23], v2, s[0:1] offset:64
	global_load_dwordx2 v[20:21], v2, s[4:5] offset:64
	ds_write_b32 v70, v3 offset:4080
	s_waitcnt vmcnt(3)
	v_lshlrev_b32_e32 v24, 16, v8
	v_and_b32_e32 v25, 0xffff0000, v8
	s_waitcnt vmcnt(2)
	v_lshlrev_b32_e32 v34, 16, v4
	v_and_b32_e32 v35, 0xffff0000, v4
	v_fma_f32 v36, |v24|, s40, 1.0
	v_fma_f32 v37, |v25|, s40, 1.0
	v_fma_f32 v40, |v34|, s40, 1.0
	v_fma_f32 v41, |v35|, s40, 1.0
	v_rcp_f32_e32 v36, v36
	v_rcp_f32_e32 v37, v37
	v_rcp_f32_e32 v40, v40
	v_rcp_f32_e32 v41, v41
	v_pk_mul_f32 v[38:39], v[24:25], v[24:25]
	v_pk_mul_f32 v[42:43], v[34:35], v[34:35]
	v_pk_mul_f32 v[38:39], v[38:39], s[64:65] op_sel_hi:[1,0]
	v_pk_fma_f32 v[44:45], v[36:37], s[42:43], v[16:17] op_sel_hi:[1,0,0]
	v_pk_mul_f32 v[42:43], v[42:43], s[64:65] op_sel_hi:[1,0]
	v_exp_f32_e32 v38, v38
	v_exp_f32_e32 v39, v39
	v_pk_fma_f32 v[46:47], v[40:41], s[42:43], v[16:17] op_sel_hi:[1,0,0]
	v_pk_fma_f32 v[44:45], v[36:37], v[44:45], s[48:49] op_sel_hi:[1,1,0]
	v_exp_f32_e32 v42, v42
	v_exp_f32_e32 v43, v43
	v_pk_fma_f32 v[46:47], v[40:41], v[46:47], s[48:49] op_sel_hi:[1,1,0]
	v_pk_fma_f32 v[44:45], v[36:37], v[44:45], s[50:51] op_sel_hi:[1,1,0]
	v_pk_fma_f32 v[46:47], v[40:41], v[46:47], s[50:51] op_sel_hi:[1,1,0]
	v_pk_fma_f32 v[44:45], v[36:37], v[44:45], s[56:57] op_sel_hi:[1,1,0]
	v_pk_fma_f32 v[46:47], v[40:41], v[46:47], s[56:57] op_sel_hi:[1,1,0]
	v_pk_mul_f32 v[36:37], v[36:37], v[44:45]
	v_pk_mul_f32 v[40:41], v[40:41], v[46:47]
	v_pk_mul_f32 v[36:37], v[38:39], v[36:37]
	v_pk_mul_f32 v[38:39], v[42:43], v[40:41]
	v_max_f32_e32 v84, 0, v24
	v_fma_f32 v3, -|v24|, v36, v84
	v_max_f32_e32 v85, 0, v25
	v_fma_f32 v4, -|v25|, v37, v85
	v_max_f32_e32 v86, 0, v34
	v_fma_f32 v8, -|v34|, v38, v86
	v_max_f32_e32 v90, 0, v35
	v_fma_f32 v24, -|v35|, v39, v90
	v_sub_f32_e32 v3, v3, v14
	v_mul_f32_e32 v3, v12, v3
	v_sub_f32_e32 v4, v4, v14
	v_mul_f32_e32 v4, v12, v4
	v_sub_f32_e32 v8, v8, v15
	v_mul_f32_e32 v8, v13, v8
	v_sub_f32_e32 v24, v24, v15
	v_mul_f32_e32 v24, v13, v24
	s_waitcnt vmcnt(0)
	v_fma_f32 v3, v22, v3, v20
	v_fma_f32 v4, v23, v4, v21
	v_fma_f32 v8, v22, v8, v20
	v_fmac_f32_e32 v21, v23, v24
	v_cvt_pk_bf16_f32 v3, v3, v8
	ds_write_b32 v70, v3 offset:4352
	v_cvt_pk_bf16_f32 v3, v4, v21
	global_load_dwordx2 v[22:23], v2, s[0:1] offset:72
	global_load_dwordx2 v[20:21], v2, s[4:5] offset:72
	v_lshlrev_b32_e32 v8, 16, v9
	v_and_b32_e32 v9, 0xffff0000, v9
	v_lshlrev_b32_e32 v4, 16, v5
	v_and_b32_e32 v5, 0xffff0000, v5
	v_fma_f32 v24, |v8|, s40, 1.0
	v_fma_f32 v25, |v9|, s40, 1.0
	v_fma_f32 v36, |v4|, s40, 1.0
	v_fma_f32 v37, |v5|, s40, 1.0
	v_rcp_f32_e32 v24, v24
	v_rcp_f32_e32 v25, v25
	v_rcp_f32_e32 v36, v36
	v_rcp_f32_e32 v37, v37
	v_pk_mul_f32 v[34:35], v[8:9], v[8:9]
	v_pk_mul_f32 v[38:39], v[4:5], v[4:5]
	v_pk_mul_f32 v[34:35], v[34:35], s[64:65] op_sel_hi:[1,0]
	v_pk_fma_f32 v[40:41], v[24:25], s[42:43], v[16:17] op_sel_hi:[1,0,0]
	v_pk_mul_f32 v[38:39], v[38:39], s[64:65] op_sel_hi:[1,0]
	v_exp_f32_e32 v34, v34
	v_exp_f32_e32 v35, v35
	v_pk_fma_f32 v[42:43], v[36:37], s[42:43], v[16:17] op_sel_hi:[1,0,0]
	v_pk_fma_f32 v[40:41], v[24:25], v[40:41], s[48:49] op_sel_hi:[1,1,0]
	v_exp_f32_e32 v38, v38
	v_exp_f32_e32 v39, v39
	v_pk_fma_f32 v[42:43], v[36:37], v[42:43], s[48:49] op_sel_hi:[1,1,0]
	v_pk_fma_f32 v[40:41], v[24:25], v[40:41], s[50:51] op_sel_hi:[1,1,0]
	v_pk_fma_f32 v[42:43], v[36:37], v[42:43], s[50:51] op_sel_hi:[1,1,0]
	v_pk_fma_f32 v[40:41], v[24:25], v[40:41], s[56:57] op_sel_hi:[1,1,0]
	v_pk_fma_f32 v[42:43], v[36:37], v[42:43], s[56:57] op_sel_hi:[1,1,0]
	v_pk_mul_f32 v[24:25], v[24:25], v[40:41]
	v_pk_mul_f32 v[36:37], v[36:37], v[42:43]
	v_pk_mul_f32 v[24:25], v[34:35], v[24:25]
	v_pk_mul_f32 v[34:35], v[38:39], v[36:37]
	v_max_f32_e32 v91, 0, v8
	v_fma_f32 v8, -|v8|, v24, v91
	v_max_f32_e32 v92, 0, v9
	v_fma_f32 v9, -|v9|, v25, v92
	v_max_f32_e32 v93, 0, v4
	v_fma_f32 v4, -|v4|, v34, v93
	v_max_f32_e32 v94, 0, v5
	v_fma_f32 v5, -|v5|, v35, v94
	v_sub_f32_e32 v8, v8, v14
	v_mul_f32_e32 v8, v12, v8
	v_sub_f32_e32 v9, v9, v14
	v_mul_f32_e32 v9, v12, v9
	v_sub_f32_e32 v4, v4, v15
	v_mul_f32_e32 v4, v13, v4
	v_sub_f32_e32 v5, v5, v15
	ds_write_b32 v70, v3 offset:4624
	v_mul_f32_e32 v5, v13, v5
	s_waitcnt vmcnt(0)
	v_fma_f32 v3, v22, v8, v20
	v_fma_f32 v8, v23, v9, v21
	v_fma_f32 v4, v22, v4, v20
	v_cvt_pk_bf16_f32 v3, v3, v4
	v_fmac_f32_e32 v21, v23, v5
	ds_write_b32 v70, v3 offset:4896
	v_cvt_pk_bf16_f32 v3, v8, v21
	global_load_dwordx2 v[8:9], v2, s[0:1] offset:80
	global_load_dwordx2 v[4:5], v2, s[4:5] offset:80
	v_lshlrev_b32_e32 v20, 16, v10
	v_and_b32_e32 v21, 0xffff0000, v10
	v_lshlrev_b32_e32 v22, 16, v6
	v_and_b32_e32 v23, 0xffff0000, v6
	v_fma_f32 v24, |v20|, s40, 1.0
	v_fma_f32 v25, |v21|, s40, 1.0
	v_fma_f32 v36, |v22|, s40, 1.0
	v_fma_f32 v37, |v23|, s40, 1.0
	v_rcp_f32_e32 v24, v24
	v_rcp_f32_e32 v25, v25
	v_rcp_f32_e32 v36, v36
	v_rcp_f32_e32 v37, v37
	v_pk_mul_f32 v[34:35], v[20:21], v[20:21]
	v_pk_mul_f32 v[38:39], v[22:23], v[22:23]
	v_pk_mul_f32 v[34:35], v[34:35], s[64:65] op_sel_hi:[1,0]
	v_pk_fma_f32 v[40:41], v[24:25], s[42:43], v[16:17] op_sel_hi:[1,0,0]
	v_pk_mul_f32 v[38:39], v[38:39], s[64:65] op_sel_hi:[1,0]
	v_exp_f32_e32 v34, v34
	v_exp_f32_e32 v35, v35
	v_pk_fma_f32 v[42:43], v[36:37], s[42:43], v[16:17] op_sel_hi:[1,0,0]
	v_pk_fma_f32 v[40:41], v[24:25], v[40:41], s[48:49] op_sel_hi:[1,1,0]
	v_exp_f32_e32 v38, v38
	v_exp_f32_e32 v39, v39
	v_pk_fma_f32 v[42:43], v[36:37], v[42:43], s[48:49] op_sel_hi:[1,1,0]
	v_pk_fma_f32 v[40:41], v[24:25], v[40:41], s[50:51] op_sel_hi:[1,1,0]
	v_pk_fma_f32 v[42:43], v[36:37], v[42:43], s[50:51] op_sel_hi:[1,1,0]
	v_pk_fma_f32 v[40:41], v[24:25], v[40:41], s[56:57] op_sel_hi:[1,1,0]
	v_pk_fma_f32 v[42:43], v[36:37], v[42:43], s[56:57] op_sel_hi:[1,1,0]
	v_pk_mul_f32 v[24:25], v[24:25], v[40:41]
	v_pk_mul_f32 v[36:37], v[36:37], v[42:43]
	v_pk_mul_f32 v[24:25], v[34:35], v[24:25]
	v_pk_mul_f32 v[34:35], v[38:39], v[36:37]
	v_max_f32_e32 v95, 0, v20
	v_fma_f32 v6, -|v20|, v24, v95
	v_max_f32_e32 v96, 0, v21
	v_fma_f32 v10, -|v21|, v25, v96
	v_max_f32_e32 v97, 0, v22
	v_fma_f32 v20, -|v22|, v34, v97
	v_max_f32_e32 v98, 0, v23
	v_fma_f32 v21, -|v23|, v35, v98
	v_sub_f32_e32 v6, v6, v14
	v_mul_f32_e32 v6, v12, v6
	v_sub_f32_e32 v10, v10, v14
	v_mul_f32_e32 v10, v12, v10
	v_sub_f32_e32 v20, v20, v15
	v_mul_f32_e32 v20, v13, v20
	v_sub_f32_e32 v21, v21, v15
	v_mul_f32_e32 v21, v13, v21
	ds_write_b32 v70, v3 offset:5168
	s_waitcnt vmcnt(0)
	v_fma_f32 v3, v8, v6, v4
	v_fma_f32 v6, v9, v10, v5
	v_fma_f32 v4, v8, v20, v4
	v_fmac_f32_e32 v5, v9, v21
	v_cvt_pk_bf16_f32 v3, v3, v4
	ds_write_b32 v70, v3 offset:5440
	v_cvt_pk_bf16_f32 v3, v6, v5
	global_load_dwordx2 v[8:9], v2, s[0:1] offset:88
	global_load_dwordx2 v[4:5], v2, s[4:5] offset:88
	v_lshlrev_b32_e32 v10, 16, v11
	v_and_b32_e32 v11, 0xffff0000, v11
	v_lshlrev_b32_e32 v6, 16, v7
	v_and_b32_e32 v7, 0xffff0000, v7
	v_fma_f32 v20, |v10|, s40, 1.0
	v_fma_f32 v21, |v11|, s40, 1.0
	v_fma_f32 v24, |v6|, s40, 1.0
	v_fma_f32 v25, |v7|, s40, 1.0
	v_rcp_f32_e32 v20, v20
	v_rcp_f32_e32 v21, v21
	v_rcp_f32_e32 v24, v24
	v_rcp_f32_e32 v25, v25
	v_pk_mul_f32 v[22:23], v[10:11], v[10:11]
	v_pk_mul_f32 v[34:35], v[6:7], v[6:7]
	v_pk_mul_f32 v[22:23], v[22:23], s[64:65] op_sel_hi:[1,0]
	v_pk_fma_f32 v[36:37], v[20:21], s[42:43], v[16:17] op_sel_hi:[1,0,0]
	v_pk_mul_f32 v[34:35], v[34:35], s[64:65] op_sel_hi:[1,0]
	v_exp_f32_e32 v22, v22
	v_exp_f32_e32 v23, v23
	v_pk_fma_f32 v[38:39], v[24:25], s[42:43], v[16:17] op_sel_hi:[1,0,0]
	v_pk_fma_f32 v[36:37], v[20:21], v[36:37], s[48:49] op_sel_hi:[1,1,0]
	v_exp_f32_e32 v34, v34
	v_exp_f32_e32 v35, v35
	v_pk_fma_f32 v[38:39], v[24:25], v[38:39], s[48:49] op_sel_hi:[1,1,0]
	v_pk_fma_f32 v[36:37], v[20:21], v[36:37], s[50:51] op_sel_hi:[1,1,0]
	v_pk_fma_f32 v[38:39], v[24:25], v[38:39], s[50:51] op_sel_hi:[1,1,0]
	v_pk_fma_f32 v[36:37], v[20:21], v[36:37], s[56:57] op_sel_hi:[1,1,0]
	v_pk_fma_f32 v[38:39], v[24:25], v[38:39], s[56:57] op_sel_hi:[1,1,0]
	v_pk_mul_f32 v[20:21], v[20:21], v[36:37]
	v_pk_mul_f32 v[24:25], v[24:25], v[38:39]
	v_pk_mul_f32 v[20:21], v[22:23], v[20:21]
	v_pk_mul_f32 v[22:23], v[34:35], v[24:25]
	v_max_f32_e32 v99, 0, v10
	v_fma_f32 v10, -|v10|, v20, v99
	v_max_f32_e32 v100, 0, v11
	v_fma_f32 v11, -|v11|, v21, v100
	v_max_f32_e32 v104, 0, v6
	v_fma_f32 v6, -|v6|, v22, v104
	v_max_f32_e32 v105, 0, v7
	v_fma_f32 v7, -|v7|, v23, v105
	v_sub_f32_e32 v10, v10, v14
	v_mul_f32_e32 v10, v12, v10
	v_sub_f32_e32 v11, v11, v14
	v_mul_f32_e32 v11, v12, v11
	v_sub_f32_e32 v6, v6, v15
	v_mul_f32_e32 v6, v13, v6
	v_sub_f32_e32 v7, v7, v15
	v_mul_f32_e32 v7, v13, v7
	ds_write_b32 v70, v3 offset:5712
	s_waitcnt vmcnt(0)
	v_fma_f32 v3, v8, v10, v4
	v_fma_f32 v10, v9, v11, v5
	v_fma_f32 v4, v8, v6, v4
	v_fmac_f32_e32 v5, v9, v7
	v_cvt_pk_bf16_f32 v3, v3, v4
	ds_write_b32 v70, v3 offset:5984
	v_cvt_pk_bf16_f32 v3, v10, v5
	global_load_dwordx4 v[8:11], v[18:19], off offset:48
	global_load_dwordx4 v[4:7], v[18:19], off offset:2096
	global_load_dwordx2 v[20:21], v2, s[0:1] offset:96
	s_nop 0
	global_load_dwordx2 v[18:19], v2, s[4:5] offset:96
	ds_write_b32 v70, v3 offset:6256
	s_waitcnt vmcnt(3)
	v_lshlrev_b32_e32 v22, 16, v8
	v_and_b32_e32 v23, 0xffff0000, v8
	s_waitcnt vmcnt(2)
	v_lshlrev_b32_e32 v24, 16, v4
	v_and_b32_e32 v25, 0xffff0000, v4
	v_fma_f32 v34, |v22|, s40, 1.0
	v_fma_f32 v35, |v23|, s40, 1.0
	v_fma_f32 v38, |v24|, s40, 1.0
	v_fma_f32 v39, |v25|, s40, 1.0
	v_rcp_f32_e32 v34, v34
	v_rcp_f32_e32 v35, v35
	v_rcp_f32_e32 v38, v38
	v_rcp_f32_e32 v39, v39
	v_pk_mul_f32 v[36:37], v[22:23], v[22:23]
	v_pk_mul_f32 v[40:41], v[24:25], v[24:25]
	v_pk_mul_f32 v[36:37], v[36:37], s[64:65] op_sel_hi:[1,0]
	v_pk_fma_f32 v[42:43], v[34:35], s[42:43], v[16:17] op_sel_hi:[1,0,0]
	v_pk_mul_f32 v[40:41], v[40:41], s[64:65] op_sel_hi:[1,0]
	v_exp_f32_e32 v36, v36
	v_exp_f32_e32 v37, v37
	v_pk_fma_f32 v[44:45], v[38:39], s[42:43], v[16:17] op_sel_hi:[1,0,0]
	v_pk_fma_f32 v[42:43], v[34:35], v[42:43], s[48:49] op_sel_hi:[1,1,0]
	v_exp_f32_e32 v40, v40
	v_exp_f32_e32 v41, v41
	v_pk_fma_f32 v[44:45], v[38:39], v[44:45], s[48:49] op_sel_hi:[1,1,0]
	v_pk_fma_f32 v[42:43], v[34:35], v[42:43], s[50:51] op_sel_hi:[1,1,0]
	v_pk_fma_f32 v[44:45], v[38:39], v[44:45], s[50:51] op_sel_hi:[1,1,0]
	v_pk_fma_f32 v[42:43], v[34:35], v[42:43], s[56:57] op_sel_hi:[1,1,0]
	v_pk_fma_f32 v[44:45], v[38:39], v[44:45], s[56:57] op_sel_hi:[1,1,0]
	v_pk_mul_f32 v[34:35], v[34:35], v[42:43]
	v_pk_mul_f32 v[38:39], v[38:39], v[44:45]
	v_pk_mul_f32 v[34:35], v[36:37], v[34:35]
	v_pk_mul_f32 v[36:37], v[40:41], v[38:39]
	v_max_f32_e32 v106, 0, v22
	v_fma_f32 v3, -|v22|, v34, v106
	v_max_f32_e32 v107, 0, v23
	v_fma_f32 v4, -|v23|, v35, v107
	v_max_f32_e32 v108, 0, v24
	v_fma_f32 v8, -|v24|, v36, v108
	v_max_f32_e32 v109, 0, v25
	v_fma_f32 v22, -|v25|, v37, v109
	v_sub_f32_e32 v3, v3, v14
	v_mul_f32_e32 v3, v12, v3
	v_sub_f32_e32 v4, v4, v14
	v_mul_f32_e32 v4, v12, v4
	v_sub_f32_e32 v8, v8, v15
	v_mul_f32_e32 v8, v13, v8
	v_sub_f32_e32 v22, v22, v15
	v_mul_f32_e32 v22, v13, v22
	s_waitcnt vmcnt(0)
	v_fma_f32 v3, v20, v3, v18
	v_fma_f32 v4, v21, v4, v19
	v_fma_f32 v8, v20, v8, v18
	v_fmac_f32_e32 v19, v21, v22
	v_cvt_pk_bf16_f32 v3, v3, v8
	ds_write_b32 v70, v3 offset:6528
	v_cvt_pk_bf16_f32 v3, v4, v19
	global_load_dwordx2 v[20:21], v2, s[0:1] offset:104
	global_load_dwordx2 v[18:19], v2, s[4:5] offset:104
	v_lshlrev_b32_e32 v8, 16, v9
	v_and_b32_e32 v9, 0xffff0000, v9
	v_lshlrev_b32_e32 v4, 16, v5
	v_and_b32_e32 v5, 0xffff0000, v5
	v_fma_f32 v22, |v8|, s40, 1.0
	v_fma_f32 v23, |v9|, s40, 1.0
	v_fma_f32 v34, |v4|, s40, 1.0
	v_fma_f32 v35, |v5|, s40, 1.0
	v_rcp_f32_e32 v22, v22
	v_rcp_f32_e32 v23, v23
	v_rcp_f32_e32 v34, v34
	v_rcp_f32_e32 v35, v35
	v_pk_mul_f32 v[24:25], v[8:9], v[8:9]
	v_pk_mul_f32 v[36:37], v[4:5], v[4:5]
	v_pk_mul_f32 v[24:25], v[24:25], s[64:65] op_sel_hi:[1,0]
	v_pk_fma_f32 v[38:39], v[22:23], s[42:43], v[16:17] op_sel_hi:[1,0,0]
	v_pk_mul_f32 v[36:37], v[36:37], s[64:65] op_sel_hi:[1,0]
	v_exp_f32_e32 v24, v24
	v_exp_f32_e32 v25, v25
	v_pk_fma_f32 v[40:41], v[34:35], s[42:43], v[16:17] op_sel_hi:[1,0,0]
	v_pk_fma_f32 v[38:39], v[22:23], v[38:39], s[48:49] op_sel_hi:[1,1,0]
	v_exp_f32_e32 v36, v36
	v_exp_f32_e32 v37, v37
	v_pk_fma_f32 v[40:41], v[34:35], v[40:41], s[48:49] op_sel_hi:[1,1,0]
	v_pk_fma_f32 v[38:39], v[22:23], v[38:39], s[50:51] op_sel_hi:[1,1,0]
	v_pk_fma_f32 v[40:41], v[34:35], v[40:41], s[50:51] op_sel_hi:[1,1,0]
	v_pk_fma_f32 v[38:39], v[22:23], v[38:39], s[56:57] op_sel_hi:[1,1,0]
	v_pk_fma_f32 v[40:41], v[34:35], v[40:41], s[56:57] op_sel_hi:[1,1,0]
	v_pk_mul_f32 v[22:23], v[22:23], v[38:39]
	v_pk_mul_f32 v[34:35], v[34:35], v[40:41]
	v_pk_mul_f32 v[22:23], v[24:25], v[22:23]
	v_pk_mul_f32 v[24:25], v[36:37], v[34:35]
	v_max_f32_e32 v110, 0, v8
	v_fma_f32 v8, -|v8|, v22, v110
	v_max_f32_e32 v111, 0, v9
	v_fma_f32 v9, -|v9|, v23, v111
	v_max_f32_e32 v112, 0, v4
	v_fma_f32 v4, -|v4|, v24, v112
	v_max_f32_e32 v113, 0, v5
	v_fma_f32 v5, -|v5|, v25, v113
	v_sub_f32_e32 v8, v8, v14
	v_mul_f32_e32 v8, v12, v8
	v_sub_f32_e32 v9, v9, v14
	v_mul_f32_e32 v9, v12, v9
	v_sub_f32_e32 v4, v4, v15
	v_mul_f32_e32 v4, v13, v4
	v_sub_f32_e32 v5, v5, v15
	ds_write_b32 v70, v3 offset:6800
	v_mul_f32_e32 v5, v13, v5
	s_waitcnt vmcnt(0)
	v_fma_f32 v3, v20, v8, v18
	v_fma_f32 v8, v21, v9, v19
	v_fma_f32 v4, v20, v4, v18
	v_cvt_pk_bf16_f32 v3, v3, v4
	v_fmac_f32_e32 v19, v21, v5
	ds_write_b32 v70, v3 offset:7072
	v_cvt_pk_bf16_f32 v3, v8, v19
	global_load_dwordx2 v[8:9], v2, s[0:1] offset:112
	global_load_dwordx2 v[4:5], v2, s[4:5] offset:112
	v_lshlrev_b32_e32 v18, 16, v10
	v_and_b32_e32 v19, 0xffff0000, v10
	v_lshlrev_b32_e32 v20, 16, v6
	v_and_b32_e32 v21, 0xffff0000, v6
	v_fma_f32 v22, |v18|, s40, 1.0
	v_fma_f32 v23, |v19|, s40, 1.0
	v_fma_f32 v34, |v20|, s40, 1.0
	v_fma_f32 v35, |v21|, s40, 1.0
	v_rcp_f32_e32 v22, v22
	v_rcp_f32_e32 v23, v23
	v_rcp_f32_e32 v34, v34
	v_rcp_f32_e32 v35, v35
	v_pk_mul_f32 v[24:25], v[18:19], v[18:19]
	v_pk_mul_f32 v[36:37], v[20:21], v[20:21]
	v_pk_mul_f32 v[24:25], v[24:25], s[64:65] op_sel_hi:[1,0]
	v_pk_fma_f32 v[38:39], v[22:23], s[42:43], v[16:17] op_sel_hi:[1,0,0]
	v_pk_mul_f32 v[36:37], v[36:37], s[64:65] op_sel_hi:[1,0]
	v_exp_f32_e32 v24, v24
	v_exp_f32_e32 v25, v25
	v_pk_fma_f32 v[40:41], v[34:35], s[42:43], v[16:17] op_sel_hi:[1,0,0]
	v_pk_fma_f32 v[38:39], v[22:23], v[38:39], s[48:49] op_sel_hi:[1,1,0]
	v_exp_f32_e32 v36, v36
	v_exp_f32_e32 v37, v37
	v_pk_fma_f32 v[40:41], v[34:35], v[40:41], s[48:49] op_sel_hi:[1,1,0]
	v_pk_fma_f32 v[38:39], v[22:23], v[38:39], s[50:51] op_sel_hi:[1,1,0]
	v_pk_fma_f32 v[40:41], v[34:35], v[40:41], s[50:51] op_sel_hi:[1,1,0]
	v_pk_fma_f32 v[38:39], v[22:23], v[38:39], s[56:57] op_sel_hi:[1,1,0]
	v_pk_fma_f32 v[40:41], v[34:35], v[40:41], s[56:57] op_sel_hi:[1,1,0]
	v_pk_mul_f32 v[22:23], v[22:23], v[38:39]
	v_pk_mul_f32 v[34:35], v[34:35], v[40:41]
	v_pk_mul_f32 v[22:23], v[24:25], v[22:23]
	v_pk_mul_f32 v[24:25], v[36:37], v[34:35]
	v_max_f32_e32 v114, 0, v18
	v_fma_f32 v6, -|v18|, v22, v114
	v_max_f32_e32 v115, 0, v19
	v_fma_f32 v10, -|v19|, v23, v115
	v_max_f32_e32 v116, 0, v20
	v_fma_f32 v18, -|v20|, v24, v116
	v_max_f32_e32 v117, 0, v21
	v_fma_f32 v19, -|v21|, v25, v117
	v_sub_f32_e32 v6, v6, v14
	v_mul_f32_e32 v6, v12, v6
	v_sub_f32_e32 v10, v10, v14
	v_mul_f32_e32 v10, v12, v10
	v_sub_f32_e32 v18, v18, v15
	v_mul_f32_e32 v18, v13, v18
	v_sub_f32_e32 v19, v19, v15
	v_mul_f32_e32 v19, v13, v19
	ds_write_b32 v70, v3 offset:7344
	s_andn2_b64 vcc, exec, s[80:81]
	s_waitcnt vmcnt(0)
	v_fma_f32 v3, v8, v6, v4
	v_fma_f32 v6, v9, v10, v5
	v_fma_f32 v4, v8, v18, v4
	v_fmac_f32_e32 v5, v9, v19
	v_cvt_pk_bf16_f32 v3, v3, v4
	ds_write_b32 v70, v3 offset:7616
	v_cvt_pk_bf16_f32 v3, v6, v5
	global_load_dwordx2 v[8:9], v2, s[0:1] offset:120
	global_load_dwordx2 v[4:5], v2, s[4:5] offset:120
	v_lshlrev_b32_e32 v10, 16, v11
	v_and_b32_e32 v11, 0xffff0000, v11
	v_cndmask_b32_e64 v6, 0, 1, s[80:81]
	v_cmp_ne_u32_e64 s[4:5], 1, v6
	v_lshlrev_b32_e32 v6, 16, v7
	v_and_b32_e32 v7, 0xffff0000, v7
	v_fma_f32 v18, |v10|, s40, 1.0
	v_fma_f32 v19, |v11|, s40, 1.0
	v_rcp_f32_e32 v18, v18
	v_rcp_f32_e32 v19, v19
	v_fma_f32 v22, |v6|, s40, 1.0
	v_fma_f32 v23, |v7|, s40, 1.0
	v_pk_mul_f32 v[20:21], v[10:11], v[10:11]
	v_rcp_f32_e32 v22, v22
	v_rcp_f32_e32 v23, v23
	v_pk_mul_f32 v[20:21], v[20:21], s[64:65] op_sel_hi:[1,0]
	v_pk_fma_f32 v[34:35], v[18:19], s[42:43], v[16:17] op_sel_hi:[1,0,0]
	v_pk_mul_f32 v[24:25], v[6:7], v[6:7]
	v_exp_f32_e32 v20, v20
	v_exp_f32_e32 v21, v21
	v_pk_fma_f32 v[34:35], v[18:19], v[34:35], s[48:49] op_sel_hi:[1,1,0]
	v_pk_mul_f32 v[24:25], v[24:25], s[64:65] op_sel_hi:[1,0]
	v_pk_fma_f32 v[16:17], v[22:23], s[42:43], v[16:17] op_sel_hi:[1,0,0]
	v_pk_fma_f32 v[34:35], v[18:19], v[34:35], s[50:51] op_sel_hi:[1,1,0]
	v_exp_f32_e32 v24, v24
	v_exp_f32_e32 v25, v25
	v_pk_fma_f32 v[16:17], v[22:23], v[16:17], s[48:49] op_sel_hi:[1,1,0]
	v_pk_fma_f32 v[34:35], v[18:19], v[34:35], s[56:57] op_sel_hi:[1,1,0]
	v_pk_fma_f32 v[16:17], v[22:23], v[16:17], s[50:51] op_sel_hi:[1,1,0]
	v_pk_mul_f32 v[18:19], v[18:19], v[34:35]
	v_pk_fma_f32 v[16:17], v[22:23], v[16:17], s[56:57] op_sel_hi:[1,1,0]
	v_pk_mul_f32 v[18:19], v[20:21], v[18:19]
	v_pk_mul_f32 v[16:17], v[22:23], v[16:17]
	v_max_f32_e32 v80, 0, v10
	v_fma_f32 v10, -|v10|, v18, v80
	v_max_f32_e32 v81, 0, v11
	v_fma_f32 v11, -|v11|, v19, v81
	v_pk_mul_f32 v[16:17], v[24:25], v[16:17]
	ds_write_b32 v70, v3 offset:7888
	v_max_f32_e32 v82, 0, v6
	v_fma_f32 v6, -|v6|, v16, v82
	v_max_f32_e32 v83, 0, v7
	v_fma_f32 v7, -|v7|, v17, v83
	v_sub_f32_e32 v10, v10, v14
	v_sub_f32_e32 v11, v11, v14
	v_sub_f32_e32 v6, v6, v15
	v_mul_f32_e32 v10, v12, v10
	v_sub_f32_e32 v7, v7, v15
	v_mul_f32_e32 v11, v12, v11
	v_mul_f32_e32 v6, v13, v6
	v_mul_f32_e32 v7, v13, v7
	s_waitcnt vmcnt(0)
	v_fma_f32 v3, v8, v10, v4
	v_fma_f32 v10, v9, v11, v5
	v_fma_f32 v4, v8, v6, v4
	v_fmac_f32_e32 v5, v9, v7
	v_cvt_pk_bf16_f32 v3, v3, v4
	ds_write_b32 v70, v3 offset:8160
	v_cvt_pk_bf16_f32 v3, v10, v5
	v_lshl_add_u64 v[4:5], s[12:13], 0, v[28:29]
	ds_write_b32 v70, v3 offset:8432
	s_cbranch_vccnz .LBB0_458
	v_add_co_u32_e32 v6, vcc, 0x2688000, v4
	s_nop 1
	v_addc_co_u32_e32 v7, vcc, 0, v5, vcc
	global_load_dwordx4 v[6:9], v[6:7], off
	v_cndmask_b32_e64 v3, 0, 1, s[82:83]
	v_cmp_ne_u32_e64 s[6:7], 1, v3
	s_andn2_b64 vcc, exec, s[82:83]
	s_cbranch_vccz .LBB0_459

.LBB0_470:
	s_waitcnt vmcnt(15)
	v_lshlrev_b32_e32 v4, 16, v66
	v_and_b32_e32 v5, 0xffff0000, v66
	v_fma_f32 v74, |v4|, s40, 1.0
	v_fma_f32 v75, |v5|, s40, 1.0
	v_mov_b64_e32 v[76:77], s[44:45]
	v_rcp_f32_e32 v74, v74
	v_rcp_f32_e32 v75, v75
	s_nop 0
	v_pk_fma_f32 v[78:79], v[74:75], s[42:43], v[76:77] op_sel_hi:[1,0,0]
	s_nop 0
	v_pk_fma_f32 v[78:79], v[74:75], v[78:79], s[48:49] op_sel_hi:[1,1,0]
	s_nop 0
	v_pk_fma_f32 v[78:79], v[74:75], v[78:79], s[50:51] op_sel_hi:[1,1,0]
	s_nop 0
	v_pk_fma_f32 v[78:79], v[74:75], v[78:79], s[56:57] op_sel_hi:[1,1,0]
	s_nop 0
	v_pk_mul_f32 v[74:75], v[74:75], v[78:79]
	v_pk_mul_f32 v[78:79], v[4:5], v[4:5]
	s_nop 0
	v_pk_mul_f32 v[78:79], v[78:79], s[64:65] op_sel_hi:[1,0]
	s_nop 0
	v_exp_f32_e32 v78, v78
	v_exp_f32_e32 v79, v79
	s_nop 0
	v_pk_mul_f32 v[74:75], v[78:79], v[74:75]
	s_nop 0
	v_max_f32_e32 v84, 0, v4
	v_fma_f32 v3, -|v4|, v74, v84
	v_max_f32_e32 v85, 0, v5
	v_fma_f32 v73, -|v5|, v75, v85
	v_lshlrev_b32_e32 v4, 16, v67
	v_and_b32_e32 v5, 0xffff0000, v67
	v_fma_f32 v66, |v4|, s40, 1.0
	v_fma_f32 v67, |v5|, s40, 1.0
	v_rcp_f32_e32 v66, v66
	v_rcp_f32_e32 v67, v67
	s_nop 0
	v_pk_fma_f32 v[74:75], v[66:67], s[42:43], v[76:77] op_sel_hi:[1,0,0]
	s_nop 0
	v_pk_fma_f32 v[74:75], v[66:67], v[74:75], s[48:49] op_sel_hi:[1,1,0]
	s_nop 0
	v_pk_fma_f32 v[74:75], v[66:67], v[74:75], s[50:51] op_sel_hi:[1,1,0]
	s_nop 0
	v_pk_fma_f32 v[74:75], v[66:67], v[74:75], s[56:57] op_sel_hi:[1,1,0]
	s_nop 0
	v_pk_mul_f32 v[66:67], v[66:67], v[74:75]
	v_pk_mul_f32 v[74:75], v[4:5], v[4:5]
	s_nop 0
	v_pk_mul_f32 v[74:75], v[74:75], s[64:65] op_sel_hi:[1,0]
	s_nop 0
	v_exp_f32_e32 v74, v74
	v_exp_f32_e32 v75, v75
	s_nop 0
	v_pk_mul_f32 v[66:67], v[74:75], v[66:67]
	s_nop 0
	v_max_f32_e32 v86, 0, v4
	v_fma_f32 v66, -|v4|, v66, v86
	v_max_f32_e32 v90, 0, v5
	v_fma_f32 v5, -|v5|, v67, v90
	v_add_f32_e32 v4, v72, v22
	v_add_f32_e32 v22, v72, v25
	v_mul_f32_e32 v3, v3, v4
	v_add_f32_e32 v4, v72, v23
	v_mul_f32_e32 v5, v5, v22
	v_add_co_u32_e32 v22, vcc, 0x1506e000, v34
	v_mul_f32_e32 v4, v73, v4
	s_nop 0
	v_addc_co_u32_e32 v23, vcc, 0, v35, vcc
	v_cvt_pk_bf16_f32 v4, v3, v4
	v_add_f32_e32 v3, v72, v24
	s_and_b64 vcc, exec, s[4:5]
	v_mul_f32_e32 v3, v66, v3
	v_cvt_pk_bf16_f32 v5, v3, v5
	global_store_dwordx2 v[22:23], v[4:5], off
	s_cbranch_vccnz .LBB0_472
	ds_read_b128 v[22:25], v71 offset:4352
	s_waitcnt lgkmcnt(0)
	v_mfma_f32_16x16x32_bf16 v[22:25], v[22:25], v[6:9], 0
	s_and_b64 vcc, exec, s[6:7]
	s_cbranch_vccz .LBB0_473
	s_branch .LBB0_474

.LBB0_478:
	s_waitcnt vmcnt(15)
	v_lshlrev_b32_e32 v4, 16, v64
	v_and_b32_e32 v5, 0xffff0000, v64
	v_fma_f32 v66, |v4|, s40, 1.0
	v_fma_f32 v67, |v5|, s40, 1.0
	v_mov_b64_e32 v[74:75], s[44:45]
	v_rcp_f32_e32 v66, v66
	v_rcp_f32_e32 v67, v67
	s_nop 0
	v_pk_fma_f32 v[76:77], v[66:67], s[42:43], v[74:75] op_sel_hi:[1,0,0]
	s_nop 0
	v_pk_fma_f32 v[76:77], v[66:67], v[76:77], s[48:49] op_sel_hi:[1,1,0]
	s_nop 0
	v_pk_fma_f32 v[76:77], v[66:67], v[76:77], s[50:51] op_sel_hi:[1,1,0]
	s_nop 0
	v_pk_fma_f32 v[76:77], v[66:67], v[76:77], s[56:57] op_sel_hi:[1,1,0]
	s_nop 0
	v_pk_mul_f32 v[66:67], v[66:67], v[76:77]
	v_pk_mul_f32 v[76:77], v[4:5], v[4:5]
	s_nop 0
	v_pk_mul_f32 v[76:77], v[76:77], s[64:65] op_sel_hi:[1,0]
	s_nop 0
	v_exp_f32_e32 v76, v76
	v_exp_f32_e32 v77, v77
	s_nop 0
	v_pk_mul_f32 v[66:67], v[76:77], v[66:67]
	s_nop 0
	v_max_f32_e32 v91, 0, v4
	v_fma_f32 v3, -|v4|, v66, v91
	v_max_f32_e32 v92, 0, v5
	v_fma_f32 v73, -|v5|, v67, v92
	v_lshlrev_b32_e32 v4, 16, v65
	v_and_b32_e32 v5, 0xffff0000, v65
	v_fma_f32 v64, |v4|, s40, 1.0
	v_fma_f32 v65, |v5|, s40, 1.0
	v_rcp_f32_e32 v64, v64
	v_rcp_f32_e32 v65, v65
	s_nop 0
	v_pk_fma_f32 v[66:67], v[64:65], s[42:43], v[74:75] op_sel_hi:[1,0,0]
	s_nop 0
	v_pk_fma_f32 v[66:67], v[64:65], v[66:67], s[48:49] op_sel_hi:[1,1,0]
	s_nop 0
	v_pk_fma_f32 v[66:67], v[64:65], v[66:67], s[50:51] op_sel_hi:[1,1,0]
	s_nop 0
	v_pk_fma_f32 v[66:67], v[64:65], v[66:67], s[56:57] op_sel_hi:[1,1,0]
	s_nop 0
	v_pk_mul_f32 v[64:65], v[64:65], v[66:67]
	v_pk_mul_f32 v[66:67], v[4:5], v[4:5]
	s_nop 0
	v_pk_mul_f32 v[66:67], v[66:67], s[64:65] op_sel_hi:[1,0]
	s_nop 0
	v_exp_f32_e32 v66, v66
	v_exp_f32_e32 v67, v67
	s_nop 0
	v_pk_mul_f32 v[64:65], v[66:67], v[64:65]
	s_nop 0
	v_max_f32_e32 v93, 0, v4
	v_fma_f32 v64, -|v4|, v64, v93
	v_max_f32_e32 v94, 0, v5
	v_fma_f32 v5, -|v5|, v65, v94
	v_add_f32_e32 v4, v72, v22
	v_add_f32_e32 v22, v72, v25
	v_mul_f32_e32 v3, v3, v4
	v_add_f32_e32 v4, v72, v23
	v_mul_f32_e32 v5, v5, v22
	v_add_co_u32_e32 v22, vcc, 0x1506e000, v34
	v_mul_f32_e32 v4, v73, v4
	s_nop 0
	v_addc_co_u32_e32 v23, vcc, 0, v35, vcc
	v_cvt_pk_bf16_f32 v4, v3, v4
	v_add_f32_e32 v3, v72, v24
	s_and_b64 vcc, exec, s[4:5]
	v_mul_f32_e32 v3, v64, v3
	v_cvt_pk_bf16_f32 v5, v3, v5
	global_store_dwordx2 v[22:23], v[4:5], off offset:32
	s_cbranch_vccnz .LBB0_480
	ds_read_b128 v[22:25], v71 offset:8704
	s_waitcnt lgkmcnt(0)
	v_mfma_f32_16x16x32_bf16 v[22:25], v[22:25], v[6:9], 0
	s_and_b64 vcc, exec, s[6:7]
	s_cbranch_vccz .LBB0_481
	s_branch .LBB0_482

.LBB0_486:
	s_waitcnt vmcnt(15)
	v_lshlrev_b32_e32 v4, 16, v62
	v_and_b32_e32 v5, 0xffff0000, v62
	v_fma_f32 v64, |v4|, s40, 1.0
	v_fma_f32 v65, |v5|, s40, 1.0
	v_mov_b64_e32 v[66:67], s[44:45]
	v_rcp_f32_e32 v64, v64
	v_rcp_f32_e32 v65, v65
	s_nop 0
	v_pk_fma_f32 v[74:75], v[64:65], s[42:43], v[66:67] op_sel_hi:[1,0,0]
	s_nop 0
	v_pk_fma_f32 v[74:75], v[64:65], v[74:75], s[48:49] op_sel_hi:[1,1,0]
	s_nop 0
	v_pk_fma_f32 v[74:75], v[64:65], v[74:75], s[50:51] op_sel_hi:[1,1,0]
	s_nop 0
	v_pk_fma_f32 v[74:75], v[64:65], v[74:75], s[56:57] op_sel_hi:[1,1,0]
	s_nop 0
	v_pk_mul_f32 v[64:65], v[64:65], v[74:75]
	v_pk_mul_f32 v[74:75], v[4:5], v[4:5]
	s_nop 0
	v_pk_mul_f32 v[74:75], v[74:75], s[64:65] op_sel_hi:[1,0]
	s_nop 0
	v_exp_f32_e32 v74, v74
	v_exp_f32_e32 v75, v75
	s_nop 0
	v_pk_mul_f32 v[64:65], v[74:75], v[64:65]
	s_nop 0
	v_max_f32_e32 v95, 0, v4
	v_fma_f32 v3, -|v4|, v64, v95
	v_max_f32_e32 v96, 0, v5
	v_fma_f32 v73, -|v5|, v65, v96
	v_lshlrev_b32_e32 v4, 16, v63
	v_and_b32_e32 v5, 0xffff0000, v63
	v_fma_f32 v62, |v4|, s40, 1.0
	v_fma_f32 v63, |v5|, s40, 1.0
	v_rcp_f32_e32 v62, v62
	v_rcp_f32_e32 v63, v63
	s_nop 0
	v_pk_fma_f32 v[64:65], v[62:63], s[42:43], v[66:67] op_sel_hi:[1,0,0]
	s_nop 0
	v_pk_fma_f32 v[64:65], v[62:63], v[64:65], s[48:49] op_sel_hi:[1,1,0]
	s_nop 0
	v_pk_fma_f32 v[64:65], v[62:63], v[64:65], s[50:51] op_sel_hi:[1,1,0]
	s_nop 0
	v_pk_fma_f32 v[64:65], v[62:63], v[64:65], s[56:57] op_sel_hi:[1,1,0]
	s_nop 0
	v_pk_mul_f32 v[62:63], v[62:63], v[64:65]
	v_pk_mul_f32 v[64:65], v[4:5], v[4:5]
	s_nop 0
	v_pk_mul_f32 v[64:65], v[64:65], s[64:65] op_sel_hi:[1,0]
	s_nop 0
	v_exp_f32_e32 v64, v64
	v_exp_f32_e32 v65, v65
	s_nop 0
	v_pk_mul_f32 v[62:63], v[64:65], v[62:63]
	s_nop 0
	v_max_f32_e32 v97, 0, v4
	v_fma_f32 v62, -|v4|, v62, v97
	v_max_f32_e32 v98, 0, v5
	v_fma_f32 v5, -|v5|, v63, v98
	v_add_f32_e32 v4, v72, v22
	v_add_f32_e32 v22, v72, v25
	v_mul_f32_e32 v3, v3, v4
	v_add_f32_e32 v4, v72, v23
	v_mul_f32_e32 v5, v5, v22
	v_add_co_u32_e32 v22, vcc, 0x1506e000, v34
	v_mul_f32_e32 v4, v73, v4
	s_nop 0
	v_addc_co_u32_e32 v23, vcc, 0, v35, vcc
	v_cvt_pk_bf16_f32 v4, v3, v4
	v_add_f32_e32 v3, v72, v24
	s_and_b64 vcc, exec, s[4:5]
	v_mul_f32_e32 v3, v62, v3
	v_cvt_pk_bf16_f32 v5, v3, v5
	global_store_dwordx2 v[22:23], v[4:5], off offset:64
	s_cbranch_vccnz .LBB0_488
	ds_read_b128 v[22:25], v71 offset:13056
	s_waitcnt lgkmcnt(0)
	v_mfma_f32_16x16x32_bf16 v[22:25], v[22:25], v[6:9], 0
	s_and_b64 vcc, exec, s[6:7]
	s_cbranch_vccz .LBB0_489
	s_branch .LBB0_490

.LBB0_494:
	s_waitcnt vmcnt(15)
	v_lshlrev_b32_e32 v4, 16, v60
	v_and_b32_e32 v5, 0xffff0000, v60
	v_fma_f32 v62, |v4|, s40, 1.0
	v_fma_f32 v63, |v5|, s40, 1.0
	v_mov_b64_e32 v[64:65], s[44:45]
	v_rcp_f32_e32 v62, v62
	v_rcp_f32_e32 v63, v63
	s_nop 0
	v_pk_fma_f32 v[66:67], v[62:63], s[42:43], v[64:65] op_sel_hi:[1,0,0]
	s_nop 0
	v_pk_fma_f32 v[66:67], v[62:63], v[66:67], s[48:49] op_sel_hi:[1,1,0]
	s_nop 0
	v_pk_fma_f32 v[66:67], v[62:63], v[66:67], s[50:51] op_sel_hi:[1,1,0]
	s_nop 0
	v_pk_fma_f32 v[66:67], v[62:63], v[66:67], s[56:57] op_sel_hi:[1,1,0]
	s_nop 0
	v_pk_mul_f32 v[62:63], v[62:63], v[66:67]
	v_pk_mul_f32 v[66:67], v[4:5], v[4:5]
	s_nop 0
	v_pk_mul_f32 v[66:67], v[66:67], s[64:65] op_sel_hi:[1,0]
	s_nop 0
	v_exp_f32_e32 v66, v66
	v_exp_f32_e32 v67, v67
	s_nop 0
	v_pk_mul_f32 v[62:63], v[66:67], v[62:63]
	s_nop 0
	v_max_f32_e32 v99, 0, v4
	v_fma_f32 v3, -|v4|, v62, v99
	v_max_f32_e32 v100, 0, v5
	v_fma_f32 v66, -|v5|, v63, v100
	v_lshlrev_b32_e32 v4, 16, v61
	v_and_b32_e32 v5, 0xffff0000, v61
	v_fma_f32 v60, |v4|, s40, 1.0
	v_fma_f32 v61, |v5|, s40, 1.0
	v_rcp_f32_e32 v60, v60
	v_rcp_f32_e32 v61, v61
	s_nop 0
	v_pk_fma_f32 v[62:63], v[60:61], s[42:43], v[64:65] op_sel_hi:[1,0,0]
	s_nop 0
	v_pk_fma_f32 v[62:63], v[60:61], v[62:63], s[48:49] op_sel_hi:[1,1,0]
	s_nop 0
	v_pk_fma_f32 v[62:63], v[60:61], v[62:63], s[50:51] op_sel_hi:[1,1,0]
	s_nop 0
	v_pk_fma_f32 v[62:63], v[60:61], v[62:63], s[56:57] op_sel_hi:[1,1,0]
	s_nop 0
	v_pk_mul_f32 v[60:61], v[60:61], v[62:63]
	v_pk_mul_f32 v[62:63], v[4:5], v[4:5]
	s_nop 0
	v_pk_mul_f32 v[62:63], v[62:63], s[64:65] op_sel_hi:[1,0]
	s_nop 0
	v_exp_f32_e32 v62, v62
	v_exp_f32_e32 v63, v63
	s_nop 0
	v_pk_mul_f32 v[60:61], v[62:63], v[60:61]
	s_nop 0
	v_max_f32_e32 v104, 0, v4
	v_fma_f32 v60, -|v4|, v60, v104
	v_max_f32_e32 v105, 0, v5
	v_fma_f32 v5, -|v5|, v61, v105
	v_add_f32_e32 v4, v72, v22
	v_add_f32_e32 v22, v72, v25
	v_mul_f32_e32 v3, v3, v4
	v_add_f32_e32 v4, v72, v23
	v_mul_f32_e32 v5, v5, v22
	v_add_co_u32_e32 v22, vcc, 0x1506e000, v34
	v_mul_f32_e32 v4, v66, v4
	s_nop 0
	v_addc_co_u32_e32 v23, vcc, 0, v35, vcc
	v_cvt_pk_bf16_f32 v4, v3, v4
	v_add_f32_e32 v3, v72, v24
	s_and_b64 vcc, exec, s[4:5]
	v_mul_f32_e32 v3, v60, v3
	v_cvt_pk_bf16_f32 v5, v3, v5
	global_store_dwordx2 v[22:23], v[4:5], off offset:96
	s_cbranch_vccnz .LBB0_496
	ds_read_b128 v[22:25], v71 offset:17408
	s_waitcnt lgkmcnt(0)
	v_mfma_f32_16x16x32_bf16 v[22:25], v[22:25], v[6:9], 0
	s_and_b64 vcc, exec, s[6:7]
	s_cbranch_vccz .LBB0_497
	s_branch .LBB0_498

.LBB0_502:
	s_waitcnt vmcnt(15)
	v_lshlrev_b32_e32 v4, 16, v58
	v_and_b32_e32 v5, 0xffff0000, v58
	v_fma_f32 v60, |v4|, s40, 1.0
	v_fma_f32 v61, |v5|, s40, 1.0
	v_mov_b64_e32 v[62:63], s[44:45]
	v_rcp_f32_e32 v60, v60
	v_rcp_f32_e32 v61, v61
	s_nop 0
	v_pk_fma_f32 v[64:65], v[60:61], s[42:43], v[62:63] op_sel_hi:[1,0,0]
	s_nop 0
	v_pk_fma_f32 v[64:65], v[60:61], v[64:65], s[48:49] op_sel_hi:[1,1,0]
	s_nop 0
	v_pk_fma_f32 v[64:65], v[60:61], v[64:65], s[50:51] op_sel_hi:[1,1,0]
	s_nop 0
	v_pk_fma_f32 v[64:65], v[60:61], v[64:65], s[56:57] op_sel_hi:[1,1,0]
	s_nop 0
	v_pk_mul_f32 v[60:61], v[60:61], v[64:65]
	v_pk_mul_f32 v[64:65], v[4:5], v[4:5]
	s_nop 0
	v_pk_mul_f32 v[64:65], v[64:65], s[64:65] op_sel_hi:[1,0]
	s_nop 0
	v_exp_f32_e32 v64, v64
	v_exp_f32_e32 v65, v65
	s_nop 0
	v_pk_mul_f32 v[60:61], v[64:65], v[60:61]
	s_nop 0
	v_max_f32_e32 v106, 0, v4
	v_fma_f32 v3, -|v4|, v60, v106
	v_max_f32_e32 v107, 0, v5
	v_fma_f32 v64, -|v5|, v61, v107
	v_lshlrev_b32_e32 v4, 16, v59
	v_and_b32_e32 v5, 0xffff0000, v59
	v_fma_f32 v58, |v4|, s40, 1.0
	v_fma_f32 v59, |v5|, s40, 1.0
	v_rcp_f32_e32 v58, v58
	v_rcp_f32_e32 v59, v59
	s_nop 0
	v_pk_fma_f32 v[60:61], v[58:59], s[42:43], v[62:63] op_sel_hi:[1,0,0]
	s_nop 0
	v_pk_fma_f32 v[60:61], v[58:59], v[60:61], s[48:49] op_sel_hi:[1,1,0]
	s_nop 0
	v_pk_fma_f32 v[60:61], v[58:59], v[60:61], s[50:51] op_sel_hi:[1,1,0]
	s_nop 0
	v_pk_fma_f32 v[60:61], v[58:59], v[60:61], s[56:57] op_sel_hi:[1,1,0]
	s_nop 0
	v_pk_mul_f32 v[58:59], v[58:59], v[60:61]
	v_pk_mul_f32 v[60:61], v[4:5], v[4:5]
	s_nop 0
	v_pk_mul_f32 v[60:61], v[60:61], s[64:65] op_sel_hi:[1,0]
	s_nop 0
	v_exp_f32_e32 v60, v60
	v_exp_f32_e32 v61, v61
	s_nop 0
	v_pk_mul_f32 v[58:59], v[60:61], v[58:59]
	s_nop 0
	v_max_f32_e32 v108, 0, v4
	v_fma_f32 v58, -|v4|, v58, v108
	v_max_f32_e32 v109, 0, v5
	v_fma_f32 v5, -|v5|, v59, v109
	v_add_f32_e32 v4, v72, v22
	v_add_f32_e32 v22, v72, v25
	v_mul_f32_e32 v3, v3, v4
	v_add_f32_e32 v4, v72, v23
	v_mul_f32_e32 v5, v5, v22
	v_add_co_u32_e32 v22, vcc, 0x1506e000, v34
	v_mul_f32_e32 v4, v64, v4
	s_nop 0
	v_addc_co_u32_e32 v23, vcc, 0, v35, vcc
	v_cvt_pk_bf16_f32 v4, v3, v4
	v_add_f32_e32 v3, v72, v24
	s_and_b64 vcc, exec, s[4:5]
	v_mul_f32_e32 v3, v58, v3
	v_cvt_pk_bf16_f32 v5, v3, v5
	global_store_dwordx2 v[22:23], v[4:5], off offset:128
	s_cbranch_vccnz .LBB0_504
	ds_read_b128 v[22:25], v71 offset:21760
	s_waitcnt lgkmcnt(0)
	v_mfma_f32_16x16x32_bf16 v[22:25], v[22:25], v[6:9], 0
	s_and_b64 vcc, exec, s[6:7]
	s_cbranch_vccz .LBB0_505
	s_branch .LBB0_506

.LBB0_510:
	s_waitcnt vmcnt(15)
	v_lshlrev_b32_e32 v4, 16, v56
	v_and_b32_e32 v5, 0xffff0000, v56
	v_fma_f32 v58, |v4|, s40, 1.0
	v_fma_f32 v59, |v5|, s40, 1.0
	v_mov_b64_e32 v[60:61], s[44:45]
	v_rcp_f32_e32 v58, v58
	v_rcp_f32_e32 v59, v59
	s_nop 0
	v_pk_fma_f32 v[62:63], v[58:59], s[42:43], v[60:61] op_sel_hi:[1,0,0]
	s_nop 0
	v_pk_fma_f32 v[62:63], v[58:59], v[62:63], s[48:49] op_sel_hi:[1,1,0]
	s_nop 0
	v_pk_fma_f32 v[62:63], v[58:59], v[62:63], s[50:51] op_sel_hi:[1,1,0]
	s_nop 0
	v_pk_fma_f32 v[62:63], v[58:59], v[62:63], s[56:57] op_sel_hi:[1,1,0]
	s_nop 0
	v_pk_mul_f32 v[58:59], v[58:59], v[62:63]
	v_pk_mul_f32 v[62:63], v[4:5], v[4:5]
	s_nop 0
	v_pk_mul_f32 v[62:63], v[62:63], s[64:65] op_sel_hi:[1,0]
	s_nop 0
	v_exp_f32_e32 v62, v62
	v_exp_f32_e32 v63, v63
	s_nop 0
	v_pk_mul_f32 v[58:59], v[62:63], v[58:59]
	s_nop 0
	v_max_f32_e32 v110, 0, v4
	v_fma_f32 v3, -|v4|, v58, v110
	v_max_f32_e32 v111, 0, v5
	v_fma_f32 v62, -|v5|, v59, v111
	v_lshlrev_b32_e32 v4, 16, v57
	v_and_b32_e32 v5, 0xffff0000, v57
	v_fma_f32 v56, |v4|, s40, 1.0
	v_fma_f32 v57, |v5|, s40, 1.0
	v_rcp_f32_e32 v56, v56
	v_rcp_f32_e32 v57, v57
	s_nop 0
	v_pk_fma_f32 v[58:59], v[56:57], s[42:43], v[60:61] op_sel_hi:[1,0,0]
	s_nop 0
	v_pk_fma_f32 v[58:59], v[56:57], v[58:59], s[48:49] op_sel_hi:[1,1,0]
	s_nop 0
	v_pk_fma_f32 v[58:59], v[56:57], v[58:59], s[50:51] op_sel_hi:[1,1,0]
	s_nop 0
	v_pk_fma_f32 v[58:59], v[56:57], v[58:59], s[56:57] op_sel_hi:[1,1,0]
	s_nop 0
	v_pk_mul_f32 v[56:57], v[56:57], v[58:59]
	v_pk_mul_f32 v[58:59], v[4:5], v[4:5]
	s_nop 0
	v_pk_mul_f32 v[58:59], v[58:59], s[64:65] op_sel_hi:[1,0]
	s_nop 0
	v_exp_f32_e32 v58, v58
	v_exp_f32_e32 v59, v59
	s_nop 0
	v_pk_mul_f32 v[56:57], v[58:59], v[56:57]
	s_nop 0
	v_max_f32_e32 v112, 0, v4
	v_fma_f32 v56, -|v4|, v56, v112
	v_max_f32_e32 v113, 0, v5
	v_fma_f32 v5, -|v5|, v57, v113
	v_add_f32_e32 v4, v72, v22
	v_add_f32_e32 v22, v72, v25
	v_mul_f32_e32 v3, v3, v4
	v_add_f32_e32 v4, v72, v23
	v_mul_f32_e32 v5, v5, v22
	v_add_co_u32_e32 v22, vcc, 0x1506e000, v34
	v_mul_f32_e32 v4, v62, v4
	s_nop 0
	v_addc_co_u32_e32 v23, vcc, 0, v35, vcc
	v_cvt_pk_bf16_f32 v4, v3, v4
	v_add_f32_e32 v3, v72, v24
	s_and_b64 vcc, exec, s[4:5]
	v_mul_f32_e32 v3, v56, v3
	v_cvt_pk_bf16_f32 v5, v3, v5
	global_store_dwordx2 v[22:23], v[4:5], off offset:160
	s_cbranch_vccnz .LBB0_512
	ds_read_b128 v[22:25], v71 offset:26112
	s_waitcnt lgkmcnt(0)
	v_mfma_f32_16x16x32_bf16 v[22:25], v[22:25], v[6:9], 0
	s_and_b64 vcc, exec, s[6:7]
	s_cbranch_vccz .LBB0_513
	s_branch .LBB0_514

.LBB0_518:
	s_waitcnt vmcnt(15)
	v_lshlrev_b32_e32 v4, 16, v54
	v_and_b32_e32 v5, 0xffff0000, v54
	v_fma_f32 v56, |v4|, s40, 1.0
	v_fma_f32 v57, |v5|, s40, 1.0
	v_mov_b64_e32 v[58:59], s[44:45]
	v_rcp_f32_e32 v56, v56
	v_rcp_f32_e32 v57, v57
	s_nop 0
	v_pk_fma_f32 v[60:61], v[56:57], s[42:43], v[58:59] op_sel_hi:[1,0,0]
	s_nop 0
	v_pk_fma_f32 v[60:61], v[56:57], v[60:61], s[48:49] op_sel_hi:[1,1,0]
	s_nop 0
	v_pk_fma_f32 v[60:61], v[56:57], v[60:61], s[50:51] op_sel_hi:[1,1,0]
	s_nop 0
	v_pk_fma_f32 v[60:61], v[56:57], v[60:61], s[56:57] op_sel_hi:[1,1,0]
	s_nop 0
	v_pk_mul_f32 v[56:57], v[56:57], v[60:61]
	v_pk_mul_f32 v[60:61], v[4:5], v[4:5]
	s_nop 0
	v_pk_mul_f32 v[60:61], v[60:61], s[64:65] op_sel_hi:[1,0]
	s_nop 0
	v_exp_f32_e32 v60, v60
	v_exp_f32_e32 v61, v61
	s_nop 0
	v_pk_mul_f32 v[56:57], v[60:61], v[56:57]
	s_nop 0
	v_max_f32_e32 v114, 0, v4
	v_fma_f32 v3, -|v4|, v56, v114
	v_max_f32_e32 v115, 0, v5
	v_fma_f32 v60, -|v5|, v57, v115
	v_lshlrev_b32_e32 v4, 16, v55
	v_and_b32_e32 v5, 0xffff0000, v55
	v_fma_f32 v54, |v4|, s40, 1.0
	v_fma_f32 v55, |v5|, s40, 1.0
	v_rcp_f32_e32 v54, v54
	v_rcp_f32_e32 v55, v55
	s_nop 0
	v_pk_fma_f32 v[56:57], v[54:55], s[42:43], v[58:59] op_sel_hi:[1,0,0]
	s_nop 0
	v_pk_fma_f32 v[56:57], v[54:55], v[56:57], s[48:49] op_sel_hi:[1,1,0]
	s_nop 0
	v_pk_fma_f32 v[56:57], v[54:55], v[56:57], s[50:51] op_sel_hi:[1,1,0]
	s_nop 0
	v_pk_fma_f32 v[56:57], v[54:55], v[56:57], s[56:57] op_sel_hi:[1,1,0]
	s_nop 0
	v_pk_mul_f32 v[54:55], v[54:55], v[56:57]
	v_pk_mul_f32 v[56:57], v[4:5], v[4:5]
	s_nop 0
	v_pk_mul_f32 v[56:57], v[56:57], s[64:65] op_sel_hi:[1,0]
	s_nop 0
	v_exp_f32_e32 v56, v56
	v_exp_f32_e32 v57, v57
	s_nop 0
	v_pk_mul_f32 v[54:55], v[56:57], v[54:55]
	s_nop 0
	v_max_f32_e32 v116, 0, v4
	v_fma_f32 v54, -|v4|, v54, v116
	v_max_f32_e32 v117, 0, v5
	v_fma_f32 v5, -|v5|, v55, v117
	v_add_f32_e32 v4, v72, v22
	v_add_f32_e32 v22, v72, v25
	v_mul_f32_e32 v3, v3, v4
	v_add_f32_e32 v4, v72, v23
	v_mul_f32_e32 v5, v5, v22
	v_add_co_u32_e32 v22, vcc, 0x1506e000, v34
	v_mul_f32_e32 v4, v60, v4
	s_nop 0
	v_addc_co_u32_e32 v23, vcc, 0, v35, vcc
	v_cvt_pk_bf16_f32 v4, v3, v4
	v_add_f32_e32 v3, v72, v24
	s_and_b64 vcc, exec, s[4:5]
	v_mul_f32_e32 v3, v54, v3
	v_cvt_pk_bf16_f32 v5, v3, v5
	global_store_dwordx2 v[22:23], v[4:5], off offset:192
	s_cbranch_vccnz .LBB0_520
	ds_read_b128 v[22:25], v71 offset:30464
	s_waitcnt lgkmcnt(0)
	v_mfma_f32_16x16x32_bf16 v[22:25], v[22:25], v[6:9], 0
	s_and_b64 vcc, exec, s[6:7]
	s_cbranch_vccz .LBB0_521
	s_branch .LBB0_522

.LBB0_526:
	s_waitcnt vmcnt(15)
	v_lshlrev_b32_e32 v4, 16, v52
	v_and_b32_e32 v5, 0xffff0000, v52
	v_fma_f32 v54, |v4|, s40, 1.0
	v_fma_f32 v55, |v5|, s40, 1.0
	v_mov_b64_e32 v[56:57], s[44:45]
	v_rcp_f32_e32 v54, v54
	v_rcp_f32_e32 v55, v55
	s_nop 0
	v_pk_fma_f32 v[58:59], v[54:55], s[42:43], v[56:57] op_sel_hi:[1,0,0]
	s_nop 0
	v_pk_fma_f32 v[58:59], v[54:55], v[58:59], s[48:49] op_sel_hi:[1,1,0]
	s_nop 0
	v_pk_fma_f32 v[58:59], v[54:55], v[58:59], s[50:51] op_sel_hi:[1,1,0]
	s_nop 0
	v_pk_fma_f32 v[58:59], v[54:55], v[58:59], s[56:57] op_sel_hi:[1,1,0]
	s_nop 0
	v_pk_mul_f32 v[54:55], v[54:55], v[58:59]
	v_pk_mul_f32 v[58:59], v[4:5], v[4:5]
	s_nop 0
	v_pk_mul_f32 v[58:59], v[58:59], s[64:65] op_sel_hi:[1,0]
	s_nop 0
	v_exp_f32_e32 v58, v58
	v_exp_f32_e32 v59, v59
	s_nop 0
	v_pk_mul_f32 v[54:55], v[58:59], v[54:55]
	s_nop 0
	v_max_f32_e32 v80, 0, v4
	v_fma_f32 v3, -|v4|, v54, v80
	v_max_f32_e32 v81, 0, v5
	v_fma_f32 v58, -|v5|, v55, v81
	v_lshlrev_b32_e32 v4, 16, v53
	v_and_b32_e32 v5, 0xffff0000, v53
	v_fma_f32 v52, |v4|, s40, 1.0
	v_fma_f32 v53, |v5|, s40, 1.0
	v_rcp_f32_e32 v52, v52
	v_rcp_f32_e32 v53, v53
	s_nop 0
	v_pk_fma_f32 v[54:55], v[52:53], s[42:43], v[56:57] op_sel_hi:[1,0,0]
	s_nop 0
	v_pk_fma_f32 v[54:55], v[52:53], v[54:55], s[48:49] op_sel_hi:[1,1,0]
	s_nop 0
	v_pk_fma_f32 v[54:55], v[52:53], v[54:55], s[50:51] op_sel_hi:[1,1,0]
	s_nop 0
	v_pk_fma_f32 v[54:55], v[52:53], v[54:55], s[56:57] op_sel_hi:[1,1,0]
	s_nop 0
	v_pk_mul_f32 v[52:53], v[52:53], v[54:55]
	v_pk_mul_f32 v[54:55], v[4:5], v[4:5]
	s_nop 0
	v_pk_mul_f32 v[54:55], v[54:55], s[64:65] op_sel_hi:[1,0]
	s_nop 0
	v_exp_f32_e32 v54, v54
	v_exp_f32_e32 v55, v55
	s_nop 0
	v_pk_mul_f32 v[52:53], v[54:55], v[52:53]
	s_nop 0
	v_max_f32_e32 v82, 0, v4
	v_fma_f32 v52, -|v4|, v52, v82
	v_max_f32_e32 v83, 0, v5
	v_fma_f32 v5, -|v5|, v53, v83
	v_add_f32_e32 v4, v72, v22
	v_add_f32_e32 v22, v72, v25
	v_mul_f32_e32 v3, v3, v4
	v_add_f32_e32 v4, v72, v23
	v_mul_f32_e32 v5, v5, v22
	v_add_co_u32_e32 v22, vcc, 0x1506e000, v34
	v_mul_f32_e32 v4, v58, v4
	s_nop 0
	v_addc_co_u32_e32 v23, vcc, 0, v35, vcc
	v_cvt_pk_bf16_f32 v4, v3, v4
	v_add_f32_e32 v3, v72, v24
	s_and_b64 vcc, exec, s[4:5]
	v_mul_f32_e32 v3, v52, v3
	v_cvt_pk_bf16_f32 v5, v3, v5
	global_store_dwordx2 v[22:23], v[4:5], off offset:224
	s_cbranch_vccnz .LBB0_528
	ds_read_b128 v[22:25], v71 offset:34816
	s_waitcnt lgkmcnt(0)
	v_mfma_f32_16x16x32_bf16 v[22:25], v[22:25], v[6:9], 0
	s_and_b64 vcc, exec, s[6:7]
	s_cbranch_vccz .LBB0_529
	s_branch .LBB0_530

.LBB0_534:
	s_waitcnt vmcnt(15)
	v_lshlrev_b32_e32 v4, 16, v50
	v_and_b32_e32 v5, 0xffff0000, v50
	v_fma_f32 v52, |v4|, s40, 1.0
	v_fma_f32 v53, |v5|, s40, 1.0
	v_mov_b64_e32 v[54:55], s[44:45]
	v_rcp_f32_e32 v52, v52
	v_rcp_f32_e32 v53, v53
	s_nop 0
	v_pk_fma_f32 v[56:57], v[52:53], s[42:43], v[54:55] op_sel_hi:[1,0,0]
	s_nop 0
	v_pk_fma_f32 v[56:57], v[52:53], v[56:57], s[48:49] op_sel_hi:[1,1,0]
	s_nop 0
	v_pk_fma_f32 v[56:57], v[52:53], v[56:57], s[50:51] op_sel_hi:[1,1,0]
	s_nop 0
	v_pk_fma_f32 v[56:57], v[52:53], v[56:57], s[56:57] op_sel_hi:[1,1,0]
	s_nop 0
	v_pk_mul_f32 v[52:53], v[52:53], v[56:57]
	v_pk_mul_f32 v[56:57], v[4:5], v[4:5]
	s_nop 0
	v_pk_mul_f32 v[56:57], v[56:57], s[64:65] op_sel_hi:[1,0]
	s_nop 0
	v_exp_f32_e32 v56, v56
	v_exp_f32_e32 v57, v57
	s_nop 0
	v_pk_mul_f32 v[52:53], v[56:57], v[52:53]
	s_nop 0
	v_max_f32_e32 v84, 0, v4
	v_fma_f32 v3, -|v4|, v52, v84
	v_max_f32_e32 v85, 0, v5
	v_fma_f32 v56, -|v5|, v53, v85
	v_lshlrev_b32_e32 v4, 16, v51
	v_and_b32_e32 v5, 0xffff0000, v51
	v_fma_f32 v50, |v4|, s40, 1.0
	v_fma_f32 v51, |v5|, s40, 1.0
	v_rcp_f32_e32 v50, v50
	v_rcp_f32_e32 v51, v51
	s_nop 0
	v_pk_fma_f32 v[52:53], v[50:51], s[42:43], v[54:55] op_sel_hi:[1,0,0]
	s_nop 0
	v_pk_fma_f32 v[52:53], v[50:51], v[52:53], s[48:49] op_sel_hi:[1,1,0]
	s_nop 0
	v_pk_fma_f32 v[52:53], v[50:51], v[52:53], s[50:51] op_sel_hi:[1,1,0]
	s_nop 0
	v_pk_fma_f32 v[52:53], v[50:51], v[52:53], s[56:57] op_sel_hi:[1,1,0]
	s_nop 0
	v_pk_mul_f32 v[50:51], v[50:51], v[52:53]
	v_pk_mul_f32 v[52:53], v[4:5], v[4:5]
	s_nop 0
	v_pk_mul_f32 v[52:53], v[52:53], s[64:65] op_sel_hi:[1,0]
	s_nop 0
	v_exp_f32_e32 v52, v52
	v_exp_f32_e32 v53, v53
	s_nop 0
	v_pk_mul_f32 v[50:51], v[52:53], v[50:51]
	s_nop 0
	v_max_f32_e32 v86, 0, v4
	v_fma_f32 v50, -|v4|, v50, v86
	v_max_f32_e32 v90, 0, v5
	v_fma_f32 v5, -|v5|, v51, v90
	v_add_f32_e32 v4, v72, v22
	v_add_f32_e32 v22, v72, v25
	v_mul_f32_e32 v3, v3, v4
	v_add_f32_e32 v4, v72, v23
	v_mul_f32_e32 v5, v5, v22
	v_add_co_u32_e32 v22, vcc, 0x1506e000, v34
	v_mul_f32_e32 v4, v56, v4
	s_nop 0
	v_addc_co_u32_e32 v23, vcc, 0, v35, vcc
	v_cvt_pk_bf16_f32 v4, v3, v4
	v_add_f32_e32 v3, v72, v24
	s_and_b64 vcc, exec, s[4:5]
	v_mul_f32_e32 v3, v50, v3
	v_cvt_pk_bf16_f32 v5, v3, v5
	global_store_dwordx2 v[22:23], v[4:5], off offset:256
	s_cbranch_vccnz .LBB0_536
	ds_read_b128 v[22:25], v71 offset:39168
	s_waitcnt lgkmcnt(0)
	v_mfma_f32_16x16x32_bf16 v[22:25], v[22:25], v[6:9], 0
	s_and_b64 vcc, exec, s[6:7]
	s_cbranch_vccz .LBB0_537
	s_branch .LBB0_538

.LBB0_542:
	s_waitcnt vmcnt(15)
	v_lshlrev_b32_e32 v4, 16, v48
	v_and_b32_e32 v5, 0xffff0000, v48
	v_fma_f32 v50, |v4|, s40, 1.0
	v_fma_f32 v51, |v5|, s40, 1.0
	v_mov_b64_e32 v[52:53], s[44:45]
	v_rcp_f32_e32 v50, v50
	v_rcp_f32_e32 v51, v51
	s_nop 0
	v_pk_fma_f32 v[54:55], v[50:51], s[42:43], v[52:53] op_sel_hi:[1,0,0]
	s_nop 0
	v_pk_fma_f32 v[54:55], v[50:51], v[54:55], s[48:49] op_sel_hi:[1,1,0]
	s_nop 0
	v_pk_fma_f32 v[54:55], v[50:51], v[54:55], s[50:51] op_sel_hi:[1,1,0]
	s_nop 0
	v_pk_fma_f32 v[54:55], v[50:51], v[54:55], s[56:57] op_sel_hi:[1,1,0]
	s_nop 0
	v_pk_mul_f32 v[50:51], v[50:51], v[54:55]
	v_pk_mul_f32 v[54:55], v[4:5], v[4:5]
	s_nop 0
	v_pk_mul_f32 v[54:55], v[54:55], s[64:65] op_sel_hi:[1,0]
	s_nop 0
	v_exp_f32_e32 v54, v54
	v_exp_f32_e32 v55, v55
	s_nop 0
	v_pk_mul_f32 v[50:51], v[54:55], v[50:51]
	s_nop 0
	v_max_f32_e32 v91, 0, v4
	v_fma_f32 v3, -|v4|, v50, v91
	v_max_f32_e32 v92, 0, v5
	v_fma_f32 v54, -|v5|, v51, v92
	v_lshlrev_b32_e32 v4, 16, v49
	v_and_b32_e32 v5, 0xffff0000, v49
	v_fma_f32 v48, |v4|, s40, 1.0
	v_fma_f32 v49, |v5|, s40, 1.0
	v_rcp_f32_e32 v48, v48
	v_rcp_f32_e32 v49, v49
	s_nop 0
	v_pk_fma_f32 v[50:51], v[48:49], s[42:43], v[52:53] op_sel_hi:[1,0,0]
	s_nop 0
	v_pk_fma_f32 v[50:51], v[48:49], v[50:51], s[48:49] op_sel_hi:[1,1,0]
	s_nop 0
	v_pk_fma_f32 v[50:51], v[48:49], v[50:51], s[50:51] op_sel_hi:[1,1,0]
	s_nop 0
	v_pk_fma_f32 v[50:51], v[48:49], v[50:51], s[56:57] op_sel_hi:[1,1,0]
	s_nop 0
	v_pk_mul_f32 v[48:49], v[48:49], v[50:51]
	v_pk_mul_f32 v[50:51], v[4:5], v[4:5]
	s_nop 0
	v_pk_mul_f32 v[50:51], v[50:51], s[64:65] op_sel_hi:[1,0]
	s_nop 0
	v_exp_f32_e32 v50, v50
	v_exp_f32_e32 v51, v51
	s_nop 0
	v_pk_mul_f32 v[48:49], v[50:51], v[48:49]
	s_nop 0
	v_max_f32_e32 v93, 0, v4
	v_fma_f32 v48, -|v4|, v48, v93
	v_max_f32_e32 v94, 0, v5
	v_fma_f32 v5, -|v5|, v49, v94
	v_add_f32_e32 v4, v72, v22
	v_add_f32_e32 v22, v72, v25
	v_mul_f32_e32 v3, v3, v4
	v_add_f32_e32 v4, v72, v23
	v_mul_f32_e32 v5, v5, v22
	v_add_co_u32_e32 v22, vcc, 0x1506e000, v34
	v_mul_f32_e32 v4, v54, v4
	s_nop 0
	v_addc_co_u32_e32 v23, vcc, 0, v35, vcc
	v_cvt_pk_bf16_f32 v4, v3, v4
	v_add_f32_e32 v3, v72, v24
	s_and_b64 vcc, exec, s[4:5]
	v_mul_f32_e32 v3, v48, v3
	v_cvt_pk_bf16_f32 v5, v3, v5
	global_store_dwordx2 v[22:23], v[4:5], off offset:288
	s_cbranch_vccnz .LBB0_544
	ds_read_b128 v[22:25], v71 offset:43520
	s_waitcnt lgkmcnt(0)
	v_mfma_f32_16x16x32_bf16 v[22:25], v[22:25], v[6:9], 0
	s_and_b64 vcc, exec, s[6:7]
	s_cbranch_vccz .LBB0_545
	s_branch .LBB0_546

.LBB0_550:
	s_waitcnt vmcnt(15)
	v_lshlrev_b32_e32 v4, 16, v46
	v_and_b32_e32 v5, 0xffff0000, v46
	v_fma_f32 v48, |v4|, s40, 1.0
	v_fma_f32 v49, |v5|, s40, 1.0
	v_mov_b64_e32 v[50:51], s[44:45]
	v_rcp_f32_e32 v48, v48
	v_rcp_f32_e32 v49, v49
	s_nop 0
	v_pk_fma_f32 v[52:53], v[48:49], s[42:43], v[50:51] op_sel_hi:[1,0,0]
	s_nop 0
	v_pk_fma_f32 v[52:53], v[48:49], v[52:53], s[48:49] op_sel_hi:[1,1,0]
	s_nop 0
	v_pk_fma_f32 v[52:53], v[48:49], v[52:53], s[50:51] op_sel_hi:[1,1,0]
	s_nop 0
	v_pk_fma_f32 v[52:53], v[48:49], v[52:53], s[56:57] op_sel_hi:[1,1,0]
	s_nop 0
	v_pk_mul_f32 v[48:49], v[48:49], v[52:53]
	v_pk_mul_f32 v[52:53], v[4:5], v[4:5]
	s_nop 0
	v_pk_mul_f32 v[52:53], v[52:53], s[64:65] op_sel_hi:[1,0]
	s_nop 0
	v_exp_f32_e32 v52, v52
	v_exp_f32_e32 v53, v53
	s_nop 0
	v_pk_mul_f32 v[48:49], v[52:53], v[48:49]
	s_nop 0
	v_max_f32_e32 v95, 0, v4
	v_fma_f32 v3, -|v4|, v48, v95
	v_max_f32_e32 v96, 0, v5
	v_fma_f32 v52, -|v5|, v49, v96
	v_lshlrev_b32_e32 v4, 16, v47
	v_and_b32_e32 v5, 0xffff0000, v47
	v_fma_f32 v46, |v4|, s40, 1.0
	v_fma_f32 v47, |v5|, s40, 1.0
	v_rcp_f32_e32 v46, v46
	v_rcp_f32_e32 v47, v47
	s_nop 0
	v_pk_fma_f32 v[48:49], v[46:47], s[42:43], v[50:51] op_sel_hi:[1,0,0]
	s_nop 0
	v_pk_fma_f32 v[48:49], v[46:47], v[48:49], s[48:49] op_sel_hi:[1,1,0]
	s_nop 0
	v_pk_fma_f32 v[48:49], v[46:47], v[48:49], s[50:51] op_sel_hi:[1,1,0]
	s_nop 0
	v_pk_fma_f32 v[48:49], v[46:47], v[48:49], s[56:57] op_sel_hi:[1,1,0]
	s_nop 0
	v_pk_mul_f32 v[46:47], v[46:47], v[48:49]
	v_pk_mul_f32 v[48:49], v[4:5], v[4:5]
	s_nop 0
	v_pk_mul_f32 v[48:49], v[48:49], s[64:65] op_sel_hi:[1,0]
	s_nop 0
	v_exp_f32_e32 v48, v48
	v_exp_f32_e32 v49, v49
	s_nop 0
	v_pk_mul_f32 v[46:47], v[48:49], v[46:47]
	s_nop 0
	v_max_f32_e32 v97, 0, v4
	v_fma_f32 v46, -|v4|, v46, v97
	v_max_f32_e32 v98, 0, v5
	v_fma_f32 v5, -|v5|, v47, v98
	v_add_f32_e32 v4, v72, v22
	v_add_f32_e32 v22, v72, v25
	v_mul_f32_e32 v3, v3, v4
	v_add_f32_e32 v4, v72, v23
	v_mul_f32_e32 v5, v5, v22
	v_add_co_u32_e32 v22, vcc, 0x1506e000, v34
	v_mul_f32_e32 v4, v52, v4
	s_nop 0
	v_addc_co_u32_e32 v23, vcc, 0, v35, vcc
	v_cvt_pk_bf16_f32 v4, v3, v4
	v_add_f32_e32 v3, v72, v24
	s_and_b64 vcc, exec, s[4:5]
	v_mul_f32_e32 v3, v46, v3
	v_cvt_pk_bf16_f32 v5, v3, v5
	global_store_dwordx2 v[22:23], v[4:5], off offset:320
	s_cbranch_vccnz .LBB0_552
	ds_read_b128 v[22:25], v71 offset:47872
	s_waitcnt lgkmcnt(0)
	v_mfma_f32_16x16x32_bf16 v[22:25], v[22:25], v[6:9], 0
	s_and_b64 vcc, exec, s[6:7]
	s_cbranch_vccz .LBB0_553
	s_branch .LBB0_554

.LBB0_558:
	s_waitcnt vmcnt(15)
	v_lshlrev_b32_e32 v4, 16, v44
	v_and_b32_e32 v5, 0xffff0000, v44
	v_fma_f32 v46, |v4|, s40, 1.0
	v_fma_f32 v47, |v5|, s40, 1.0
	v_mov_b64_e32 v[48:49], s[44:45]
	v_rcp_f32_e32 v46, v46
	v_rcp_f32_e32 v47, v47
	s_nop 0
	v_pk_fma_f32 v[50:51], v[46:47], s[42:43], v[48:49] op_sel_hi:[1,0,0]
	s_nop 0
	v_pk_fma_f32 v[50:51], v[46:47], v[50:51], s[48:49] op_sel_hi:[1,1,0]
	s_nop 0
	v_pk_fma_f32 v[50:51], v[46:47], v[50:51], s[50:51] op_sel_hi:[1,1,0]
	s_nop 0
	v_pk_fma_f32 v[50:51], v[46:47], v[50:51], s[56:57] op_sel_hi:[1,1,0]
	s_nop 0
	v_pk_mul_f32 v[46:47], v[46:47], v[50:51]
	v_pk_mul_f32 v[50:51], v[4:5], v[4:5]
	s_nop 0
	v_pk_mul_f32 v[50:51], v[50:51], s[64:65] op_sel_hi:[1,0]
	s_nop 0
	v_exp_f32_e32 v50, v50
	v_exp_f32_e32 v51, v51
	s_nop 0
	v_pk_mul_f32 v[46:47], v[50:51], v[46:47]
	s_nop 0
	v_max_f32_e32 v99, 0, v4
	v_fma_f32 v3, -|v4|, v46, v99
	v_max_f32_e32 v100, 0, v5
	v_fma_f32 v50, -|v5|, v47, v100
	v_lshlrev_b32_e32 v4, 16, v45
	v_and_b32_e32 v5, 0xffff0000, v45
	v_fma_f32 v44, |v4|, s40, 1.0
	v_fma_f32 v45, |v5|, s40, 1.0
	v_rcp_f32_e32 v44, v44
	v_rcp_f32_e32 v45, v45
	s_nop 0
	v_pk_fma_f32 v[46:47], v[44:45], s[42:43], v[48:49] op_sel_hi:[1,0,0]
	s_nop 0
	v_pk_fma_f32 v[46:47], v[44:45], v[46:47], s[48:49] op_sel_hi:[1,1,0]
	s_nop 0
	v_pk_fma_f32 v[46:47], v[44:45], v[46:47], s[50:51] op_sel_hi:[1,1,0]
	s_nop 0
	v_pk_fma_f32 v[46:47], v[44:45], v[46:47], s[56:57] op_sel_hi:[1,1,0]
	s_nop 0
	v_pk_mul_f32 v[44:45], v[44:45], v[46:47]
	v_pk_mul_f32 v[46:47], v[4:5], v[4:5]
	s_nop 0
	v_pk_mul_f32 v[46:47], v[46:47], s[64:65] op_sel_hi:[1,0]
	s_nop 0
	v_exp_f32_e32 v46, v46
	v_exp_f32_e32 v47, v47
	s_nop 0
	v_pk_mul_f32 v[44:45], v[46:47], v[44:45]
	s_nop 0
	v_max_f32_e32 v104, 0, v4
	v_fma_f32 v44, -|v4|, v44, v104
	v_max_f32_e32 v105, 0, v5
	v_fma_f32 v5, -|v5|, v45, v105
	v_add_f32_e32 v4, v72, v22
	v_add_f32_e32 v22, v72, v25
	v_mul_f32_e32 v3, v3, v4
	v_add_f32_e32 v4, v72, v23
	v_mul_f32_e32 v5, v5, v22
	v_add_co_u32_e32 v22, vcc, 0x1506e000, v34
	v_mul_f32_e32 v4, v50, v4
	s_nop 0
	v_addc_co_u32_e32 v23, vcc, 0, v35, vcc
	v_cvt_pk_bf16_f32 v4, v3, v4
	v_add_f32_e32 v3, v72, v24
	s_and_b64 vcc, exec, s[4:5]
	v_mul_f32_e32 v3, v44, v3
	v_cvt_pk_bf16_f32 v5, v3, v5
	global_store_dwordx2 v[22:23], v[4:5], off offset:352
	s_cbranch_vccnz .LBB0_560
	ds_read_b128 v[22:25], v71 offset:52224
	s_waitcnt lgkmcnt(0)
	v_mfma_f32_16x16x32_bf16 v[22:25], v[22:25], v[6:9], 0
	s_and_b64 vcc, exec, s[6:7]
	s_cbranch_vccz .LBB0_561
	s_branch .LBB0_562

.LBB0_566:
	s_waitcnt vmcnt(15)
	v_lshlrev_b32_e32 v4, 16, v42
	v_and_b32_e32 v5, 0xffff0000, v42
	v_fma_f32 v44, |v4|, s40, 1.0
	v_fma_f32 v45, |v5|, s40, 1.0
	v_mov_b64_e32 v[46:47], s[44:45]
	v_rcp_f32_e32 v44, v44
	v_rcp_f32_e32 v45, v45
	s_nop 0
	v_pk_fma_f32 v[48:49], v[44:45], s[42:43], v[46:47] op_sel_hi:[1,0,0]
	s_nop 0
	v_pk_fma_f32 v[48:49], v[44:45], v[48:49], s[48:49] op_sel_hi:[1,1,0]
	s_nop 0
	v_pk_fma_f32 v[48:49], v[44:45], v[48:49], s[50:51] op_sel_hi:[1,1,0]
	s_nop 0
	v_pk_fma_f32 v[48:49], v[44:45], v[48:49], s[56:57] op_sel_hi:[1,1,0]
	s_nop 0
	v_pk_mul_f32 v[44:45], v[44:45], v[48:49]
	v_pk_mul_f32 v[48:49], v[4:5], v[4:5]
	s_nop 0
	v_pk_mul_f32 v[48:49], v[48:49], s[64:65] op_sel_hi:[1,0]
	s_nop 0
	v_exp_f32_e32 v48, v48
	v_exp_f32_e32 v49, v49
	s_nop 0
	v_pk_mul_f32 v[44:45], v[48:49], v[44:45]
	s_nop 0
	v_max_f32_e32 v106, 0, v4
	v_fma_f32 v3, -|v4|, v44, v106
	v_max_f32_e32 v107, 0, v5
	v_fma_f32 v48, -|v5|, v45, v107
	v_lshlrev_b32_e32 v4, 16, v43
	v_and_b32_e32 v5, 0xffff0000, v43
	v_fma_f32 v42, |v4|, s40, 1.0
	v_fma_f32 v43, |v5|, s40, 1.0
	v_rcp_f32_e32 v42, v42
	v_rcp_f32_e32 v43, v43
	s_nop 0
	v_pk_fma_f32 v[44:45], v[42:43], s[42:43], v[46:47] op_sel_hi:[1,0,0]
	s_nop 0
	v_pk_fma_f32 v[44:45], v[42:43], v[44:45], s[48:49] op_sel_hi:[1,1,0]
	s_nop 0
	v_pk_fma_f32 v[44:45], v[42:43], v[44:45], s[50:51] op_sel_hi:[1,1,0]
	s_nop 0
	v_pk_fma_f32 v[44:45], v[42:43], v[44:45], s[56:57] op_sel_hi:[1,1,0]
	s_nop 0
	v_pk_mul_f32 v[42:43], v[42:43], v[44:45]
	v_pk_mul_f32 v[44:45], v[4:5], v[4:5]
	s_nop 0
	v_pk_mul_f32 v[44:45], v[44:45], s[64:65] op_sel_hi:[1,0]
	s_nop 0
	v_exp_f32_e32 v44, v44
	v_exp_f32_e32 v45, v45
	s_nop 0
	v_pk_mul_f32 v[42:43], v[44:45], v[42:43]
	s_nop 0
	v_max_f32_e32 v108, 0, v4
	v_fma_f32 v42, -|v4|, v42, v108
	v_max_f32_e32 v109, 0, v5
	v_fma_f32 v5, -|v5|, v43, v109
	v_add_f32_e32 v4, v72, v22
	v_add_f32_e32 v22, v72, v25
	v_mul_f32_e32 v3, v3, v4
	v_add_f32_e32 v4, v72, v23
	v_mul_f32_e32 v5, v5, v22
	v_add_co_u32_e32 v22, vcc, 0x1506e000, v34
	v_mul_f32_e32 v4, v48, v4
	s_nop 0
	v_addc_co_u32_e32 v23, vcc, 0, v35, vcc
	v_cvt_pk_bf16_f32 v4, v3, v4
	v_add_f32_e32 v3, v72, v24
	s_and_b64 vcc, exec, s[4:5]
	v_mul_f32_e32 v3, v42, v3
	v_cvt_pk_bf16_f32 v5, v3, v5
	global_store_dwordx2 v[22:23], v[4:5], off offset:384
	s_cbranch_vccnz .LBB0_568
	ds_read_b128 v[22:25], v71 offset:56576
	s_waitcnt lgkmcnt(0)
	v_mfma_f32_16x16x32_bf16 v[22:25], v[22:25], v[6:9], 0
	s_and_b64 vcc, exec, s[6:7]
	s_cbranch_vccz .LBB0_569
	s_branch .LBB0_570

.LBB0_574:
	s_waitcnt vmcnt(15)
	v_lshlrev_b32_e32 v4, 16, v40
	v_and_b32_e32 v5, 0xffff0000, v40
	v_fma_f32 v42, |v4|, s40, 1.0
	v_fma_f32 v43, |v5|, s40, 1.0
	v_mov_b64_e32 v[44:45], s[44:45]
	v_rcp_f32_e32 v42, v42
	v_rcp_f32_e32 v43, v43
	s_nop 0
	v_pk_fma_f32 v[46:47], v[42:43], s[42:43], v[44:45] op_sel_hi:[1,0,0]
	s_nop 0
	v_pk_fma_f32 v[46:47], v[42:43], v[46:47], s[48:49] op_sel_hi:[1,1,0]
	s_nop 0
	v_pk_fma_f32 v[46:47], v[42:43], v[46:47], s[50:51] op_sel_hi:[1,1,0]
	s_nop 0
	v_pk_fma_f32 v[46:47], v[42:43], v[46:47], s[56:57] op_sel_hi:[1,1,0]
	s_nop 0
	v_pk_mul_f32 v[42:43], v[42:43], v[46:47]
	v_pk_mul_f32 v[46:47], v[4:5], v[4:5]
	s_nop 0
	v_pk_mul_f32 v[46:47], v[46:47], s[64:65] op_sel_hi:[1,0]
	s_nop 0
	v_exp_f32_e32 v46, v46
	v_exp_f32_e32 v47, v47
	s_nop 0
	v_pk_mul_f32 v[42:43], v[46:47], v[42:43]
	s_nop 0
	v_max_f32_e32 v110, 0, v4
	v_fma_f32 v3, -|v4|, v42, v110
	v_max_f32_e32 v111, 0, v5
	v_fma_f32 v46, -|v5|, v43, v111
	v_lshlrev_b32_e32 v4, 16, v41
	v_and_b32_e32 v5, 0xffff0000, v41
	v_fma_f32 v40, |v4|, s40, 1.0
	v_fma_f32 v41, |v5|, s40, 1.0
	v_rcp_f32_e32 v40, v40
	v_rcp_f32_e32 v41, v41
	s_nop 0
	v_pk_fma_f32 v[42:43], v[40:41], s[42:43], v[44:45] op_sel_hi:[1,0,0]
	s_nop 0
	v_pk_fma_f32 v[42:43], v[40:41], v[42:43], s[48:49] op_sel_hi:[1,1,0]
	s_nop 0
	v_pk_fma_f32 v[42:43], v[40:41], v[42:43], s[50:51] op_sel_hi:[1,1,0]
	s_nop 0
	v_pk_fma_f32 v[42:43], v[40:41], v[42:43], s[56:57] op_sel_hi:[1,1,0]
	s_nop 0
	v_pk_mul_f32 v[40:41], v[40:41], v[42:43]
	v_pk_mul_f32 v[42:43], v[4:5], v[4:5]
	s_nop 0
	v_pk_mul_f32 v[42:43], v[42:43], s[64:65] op_sel_hi:[1,0]
	s_nop 0
	v_exp_f32_e32 v42, v42
	v_exp_f32_e32 v43, v43
	s_nop 0
	v_pk_mul_f32 v[40:41], v[42:43], v[40:41]
	s_nop 0
	v_max_f32_e32 v112, 0, v4
	v_fma_f32 v40, -|v4|, v40, v112
	v_max_f32_e32 v113, 0, v5
	v_fma_f32 v5, -|v5|, v41, v113
	v_add_f32_e32 v4, v72, v22
	v_add_f32_e32 v22, v72, v25
	v_mul_f32_e32 v3, v3, v4
	v_add_f32_e32 v4, v72, v23
	v_mul_f32_e32 v5, v5, v22
	v_add_co_u32_e32 v22, vcc, 0x1506e000, v34
	v_mul_f32_e32 v4, v46, v4
	s_nop 0
	v_addc_co_u32_e32 v23, vcc, 0, v35, vcc
	v_cvt_pk_bf16_f32 v4, v3, v4
	v_add_f32_e32 v3, v72, v24
	s_and_b64 vcc, exec, s[4:5]
	v_mul_f32_e32 v3, v40, v3
	v_cvt_pk_bf16_f32 v5, v3, v5
	global_store_dwordx2 v[22:23], v[4:5], off offset:416
	s_cbranch_vccnz .LBB0_576
	ds_read_b128 v[22:25], v71 offset:60928
	s_waitcnt lgkmcnt(0)
	v_mfma_f32_16x16x32_bf16 v[22:25], v[22:25], v[6:9], 0
	s_and_b64 vcc, exec, s[6:7]
	s_cbranch_vccz .LBB0_577
	s_branch .LBB0_578

.LBB0_582:
	s_waitcnt vmcnt(15)
	v_lshlrev_b32_e32 v4, 16, v38
	v_and_b32_e32 v5, 0xffff0000, v38
	v_fma_f32 v40, |v4|, s40, 1.0
	v_fma_f32 v41, |v5|, s40, 1.0
	v_mov_b64_e32 v[42:43], s[44:45]
	v_rcp_f32_e32 v40, v40
	v_rcp_f32_e32 v41, v41
	s_nop 0
	v_pk_fma_f32 v[44:45], v[40:41], s[42:43], v[42:43] op_sel_hi:[1,0,0]
	s_nop 0
	v_pk_fma_f32 v[44:45], v[40:41], v[44:45], s[48:49] op_sel_hi:[1,1,0]
	s_nop 0
	v_pk_fma_f32 v[44:45], v[40:41], v[44:45], s[50:51] op_sel_hi:[1,1,0]
	s_nop 0
	v_pk_fma_f32 v[44:45], v[40:41], v[44:45], s[56:57] op_sel_hi:[1,1,0]
	s_nop 0
	v_pk_mul_f32 v[40:41], v[40:41], v[44:45]
	v_pk_mul_f32 v[44:45], v[4:5], v[4:5]
	s_nop 0
	v_pk_mul_f32 v[44:45], v[44:45], s[64:65] op_sel_hi:[1,0]
	s_nop 0
	v_exp_f32_e32 v44, v44
	v_exp_f32_e32 v45, v45
	s_nop 0
	v_pk_mul_f32 v[40:41], v[44:45], v[40:41]
	s_nop 0
	v_max_f32_e32 v114, 0, v4
	v_fma_f32 v3, -|v4|, v40, v114
	v_max_f32_e32 v115, 0, v5
	v_fma_f32 v44, -|v5|, v41, v115
	v_lshlrev_b32_e32 v4, 16, v39
	v_and_b32_e32 v5, 0xffff0000, v39
	v_fma_f32 v38, |v4|, s40, 1.0
	v_fma_f32 v39, |v5|, s40, 1.0
	v_rcp_f32_e32 v38, v38
	v_rcp_f32_e32 v39, v39
	s_nop 0
	v_pk_fma_f32 v[40:41], v[38:39], s[42:43], v[42:43] op_sel_hi:[1,0,0]
	s_nop 0
	v_pk_fma_f32 v[40:41], v[38:39], v[40:41], s[48:49] op_sel_hi:[1,1,0]
	s_nop 0
	v_pk_fma_f32 v[40:41], v[38:39], v[40:41], s[50:51] op_sel_hi:[1,1,0]
	s_nop 0
	v_pk_fma_f32 v[40:41], v[38:39], v[40:41], s[56:57] op_sel_hi:[1,1,0]
	s_nop 0
	v_pk_mul_f32 v[38:39], v[38:39], v[40:41]
	v_pk_mul_f32 v[40:41], v[4:5], v[4:5]
	s_nop 0
	v_pk_mul_f32 v[40:41], v[40:41], s[64:65] op_sel_hi:[1,0]
	s_nop 0
	v_exp_f32_e32 v40, v40
	v_exp_f32_e32 v41, v41
	s_nop 0
	v_pk_mul_f32 v[38:39], v[40:41], v[38:39]
	s_nop 0
	v_max_f32_e32 v116, 0, v4
	v_fma_f32 v38, -|v4|, v38, v116
	v_max_f32_e32 v117, 0, v5
	v_fma_f32 v5, -|v5|, v39, v117
	v_add_f32_e32 v4, v72, v22
	v_add_f32_e32 v22, v72, v25
	v_mul_f32_e32 v3, v3, v4
	v_add_f32_e32 v4, v72, v23
	v_mul_f32_e32 v5, v5, v22
	v_add_co_u32_e32 v22, vcc, 0x1506e000, v34
	v_mul_f32_e32 v4, v44, v4
	s_nop 0
	v_addc_co_u32_e32 v23, vcc, 0, v35, vcc
	v_cvt_pk_bf16_f32 v4, v3, v4
	v_add_f32_e32 v3, v72, v24
	s_and_b64 vcc, exec, s[4:5]
	v_mul_f32_e32 v3, v38, v3
	v_cvt_pk_bf16_f32 v5, v3, v5
	global_store_dwordx2 v[22:23], v[4:5], off offset:448
	s_cbranch_vccnz .LBB0_584
	ds_read_b128 v[22:25], v71 offset:65280
	s_waitcnt lgkmcnt(0)
	v_mfma_f32_16x16x32_bf16 v[4:7], v[22:25], v[6:9], 0
	s_and_b64 vcc, exec, s[6:7]
	s_cbranch_vccz .LBB0_585
	s_branch .LBB0_586
